# ret_scan rq tile staged by direct global-to-LDS loads (LDS-DMA, rows stored as 1-KiB pairs) instead of register staging
# baseline (speedup 1.0000x reference)
.LBB0_320:
	v_cmp_gt_i32_e32 vcc, s10, v147
	s_and_saveexec_b64 s[8:9], vcc
	s_cbranch_execz .LBB0_332
	v_bfe_u32 v0, v11, 5, 1
	v_and_b32_e32 v146, 31, v11
	v_mul_i32_i24_e32 v149, 0x12000, v18
	s_and_b64 s[4:5], s[60:61], exec
	v_lshrrev_b32_e32 v2, 1, v11
	v_lshlrev_b32_e32 v150, 3, v0
	s_cselect_b32 s54, 8, 11
	v_and_b32_e32 v148, 0x60, v2
	v_lshlrev_b32_e32 v151, 11, v0
	v_lshlrev_b32_e32 v174, 2, v0
	v_or_b32_e32 v2, v149, v150
	v_mul_u32_u24_e32 v3, 0x108, v146
	s_add_u32 s60, s59, 0x5400000
	s_movk_i32 s4, 0x208
	v_lshlrev_b32_e32 v0, 4, v0
	v_sub_u32_e32 v175, 0x80, v174
	v_or_b32_e32 v176, 1, v174
	v_xor_b32_e32 v177, 0x7f, v150
	s_addc_u32 s61, s66, 0
	v_lshrrev_b32_e32 v178, 1, v146
	v_mul_u32_u24_e32 v178, 0x410, v178
	v_and_b32_e32 v179, 1, v146
	v_lshl_add_u32 v178, v179, 9, v178
	v_add_u32_e32 v178, v178, v2
	v_add3_u32 v179, v149, v3, v0
	v_or_b32_e32 v180, v148, v146
	s_add_i32 s55, s20, -1
	s_mov_b64 s[62:63], 0
	v_lshlrev_b32_e32 v152, 1, v150
	s_branch .LBB0_323

.LBB0_327:
	v_mov_b32_e32 v130, s67
	v_mov_b32_e32 v131, s66
	v_cndmask_b32_e32 v130, v130, v131, vcc
	v_lshl_add_u32 v168, v130, 7, v155
	v_mov_b32_e32 v153, v161
	v_mov_b32_e32 v192, v181
	v_mov_b32_e32 v190, v183
	v_mov_b32_e32 v191, v182
	v_mov_b32_e32 v166, v157
	v_mov_b32_e32 v130, v186
	v_mov_b32_e32 v131, v187
	v_ashrrev_i32_e32 v169, 31, v168
	v_readfirstlane_b32 s64, v130
	v_readfirstlane_b32 s65, v131
	v_lshlrev_b64 v[130:131], 11, v[168:169]
	v_mov_b32_e32 v167, v189
	s_barrier
	v_lshl_add_u64 v[130:131], s[64:65], 0, v[130:131]
	v_lshl_add_u64 v[130:131], v[130:131], 0, v[0:1]
	v_bfe_u32 v132, v189, 6, 2
	v_lshlrev_b32_e32 v132, 5, v132
	v_bfe_u32 v133, v189, 5, 1
	v_add_u32_e32 v132, v132, v133
	v_lshlrev_b32_e32 v132, 11, v132
	v_and_b32_e32 v133, 31, v189
	v_lshl_add_u32 v132, v133, 4, v132
	v_mov_b32_e32 v133, 0
	v_lshl_add_u64 v[130:131], v[130:131], 0, v[132:133]
	s_mov_b32 s6, 0xc640000
	s_mov_b32 s7, 0
	v_lshl_add_u64 v[130:131], v[130:131], 0, s[6:7]
	v_readfirstlane_b32 s6, v149
	v_readfirstlane_b32 s7, v189
	s_nop 3
	s_bfe_u32 s7, s7, 0x20006
	s_mul_i32 s7, s7, 0x4100
	s_add_u32 s6, s6, s7
	s_mov_b32 m0, s6
	s_mov_b32 s6, 0x1000
	s_mov_b32 s7, 0
	global_load_lds_dwordx4 v[130:131], off
	s_add_u32 m0, m0, 0x410
	v_lshl_add_u64 v[130:131], v[130:131], 0, s[6:7]
	global_load_lds_dwordx4 v[130:131], off
	s_add_u32 m0, m0, 0x410
	v_lshl_add_u64 v[130:131], v[130:131], 0, s[6:7]
	global_load_lds_dwordx4 v[130:131], off
	s_add_u32 m0, m0, 0x410
	v_lshl_add_u64 v[130:131], v[130:131], 0, s[6:7]
	global_load_lds_dwordx4 v[130:131], off
	s_add_u32 m0, m0, 0x410
	v_lshl_add_u64 v[130:131], v[130:131], 0, s[6:7]
	global_load_lds_dwordx4 v[130:131], off
	s_add_u32 m0, m0, 0x410
	v_lshl_add_u64 v[130:131], v[130:131], 0, s[6:7]
	global_load_lds_dwordx4 v[130:131], off
	s_add_u32 m0, m0, 0x410
	v_lshl_add_u64 v[130:131], v[130:131], 0, s[6:7]
	global_load_lds_dwordx4 v[130:131], off
	s_add_u32 m0, m0, 0x410
	v_lshl_add_u64 v[130:131], v[130:131], 0, s[6:7]
	global_load_lds_dwordx4 v[130:131], off
	s_add_u32 m0, m0, 0x410
	v_lshl_add_u64 v[130:131], v[130:131], 0, s[6:7]
	global_load_lds_dwordx4 v[130:131], off
	s_add_u32 m0, m0, 0x410
	v_lshl_add_u64 v[130:131], v[130:131], 0, s[6:7]
	global_load_lds_dwordx4 v[130:131], off
	s_add_u32 m0, m0, 0x410
	v_lshl_add_u64 v[130:131], v[130:131], 0, s[6:7]
	global_load_lds_dwordx4 v[130:131], off
	s_add_u32 m0, m0, 0x410
	v_lshl_add_u64 v[130:131], v[130:131], 0, s[6:7]
	global_load_lds_dwordx4 v[130:131], off
	s_add_u32 m0, m0, 0x410
	v_lshl_add_u64 v[130:131], v[130:131], 0, s[6:7]
	global_load_lds_dwordx4 v[130:131], off
	s_add_u32 m0, m0, 0x410
	v_lshl_add_u64 v[130:131], v[130:131], 0, s[6:7]
	global_load_lds_dwordx4 v[130:131], off
	s_add_u32 m0, m0, 0x410
	v_lshl_add_u64 v[130:131], v[130:131], 0, s[6:7]
	global_load_lds_dwordx4 v[130:131], off
	s_add_u32 m0, m0, 0x410
	v_lshl_add_u64 v[130:131], v[130:131], 0, s[6:7]
	global_load_lds_dwordx4 v[130:131], off
	v_lshl_add_u64 v[210:211], s[64:65], 0, v[162:163]
	s_waitcnt vmcnt(0)
	s_waitcnt lgkmcnt(0)
	s_barrier
	v_ashrrev_i32_e32 v167, 31, v166
	v_lshl_add_u64 v[130:131], v[166:167], 1, v[210:211]
	s_mov_b64 s[6:7], 0x8640000
	v_lshl_add_u64 v[170:171], v[130:131], 0, s[6:7]
	v_add_u32_e32 v250, 0x4000, v178
	ds_read2_b64 v[194:197], v178 offset0:0 offset1:2
	ds_read2_b64 v[218:221], v250 offset0:32 offset1:34
	ds_read2_b64 v[222:225], v178 offset0:4 offset1:6
	ds_read2_b64 v[226:229], v250 offset0:36 offset1:38
	s_nop 0
	v_cvt_pk_bf16_f32 v230, v2, v3
	v_cvt_pk_bf16_f32 v231, v4, v5
	v_cvt_pk_bf16_f32 v232, v6, v7
	v_cvt_pk_bf16_f32 v233, v8, v9
	s_waitcnt lgkmcnt(2)
	s_nop 1
	v_mfma_f32_32x32x16_bf16 v[130:145], v[194:197], v[230:233], 0
	v_mfma_f32_32x32x16_bf16 v[234:249], v[218:221], v[230:233], 0
	ds_read2_b64 v[194:197], v178 offset0:8 offset1:10
	ds_read2_b64 v[218:221], v250 offset0:40 offset1:42
	s_nop 0
	v_cvt_pk_bf16_f32 v230, v10, v11
	v_cvt_pk_bf16_f32 v231, v12, v13
	v_cvt_pk_bf16_f32 v232, v14, v15
	v_cvt_pk_bf16_f32 v233, v16, v17
	s_waitcnt lgkmcnt(2)
	s_nop 1
	v_mfma_f32_32x32x16_bf16 v[130:145], v[222:225], v[230:233], v[130:145]
	v_mfma_f32_32x32x16_bf16 v[234:249], v[226:229], v[230:233], v[234:249]
	ds_read2_b64 v[222:225], v178 offset0:12 offset1:14
	ds_read2_b64 v[226:229], v250 offset0:44 offset1:46
	s_nop 0
	v_cvt_pk_bf16_f32 v230, v18, v19
	v_cvt_pk_bf16_f32 v231, v20, v21
	v_cvt_pk_bf16_f32 v232, v22, v23
	v_cvt_pk_bf16_f32 v233, v24, v25
	s_waitcnt lgkmcnt(2)
	s_nop 1
	v_mfma_f32_32x32x16_bf16 v[130:145], v[194:197], v[230:233], v[130:145]
	v_mfma_f32_32x32x16_bf16 v[234:249], v[218:221], v[230:233], v[234:249]
	ds_read2_b64 v[194:197], v178 offset0:16 offset1:18
	ds_read2_b64 v[218:221], v250 offset0:48 offset1:50
	s_nop 0
	v_cvt_pk_bf16_f32 v230, v26, v27
	v_cvt_pk_bf16_f32 v231, v28, v29
	v_cvt_pk_bf16_f32 v232, v30, v31
	v_cvt_pk_bf16_f32 v233, v32, v33
	s_waitcnt lgkmcnt(2)
	s_nop 1
	v_mfma_f32_32x32x16_bf16 v[130:145], v[222:225], v[230:233], v[130:145]
	v_mfma_f32_32x32x16_bf16 v[234:249], v[226:229], v[230:233], v[234:249]
	ds_read2_b64 v[222:225], v178 offset0:20 offset1:22
	ds_read2_b64 v[226:229], v250 offset0:52 offset1:54
	s_nop 0
	v_cvt_pk_bf16_f32 v230, v34, v35
	v_cvt_pk_bf16_f32 v231, v36, v37
	v_cvt_pk_bf16_f32 v232, v38, v39
	v_cvt_pk_bf16_f32 v233, v40, v41
	s_waitcnt lgkmcnt(2)
	s_nop 1
	v_mfma_f32_32x32x16_bf16 v[130:145], v[194:197], v[230:233], v[130:145]
	v_mfma_f32_32x32x16_bf16 v[234:249], v[218:221], v[230:233], v[234:249]
	ds_read2_b64 v[194:197], v178 offset0:24 offset1:26
	ds_read2_b64 v[218:221], v250 offset0:56 offset1:58
	s_nop 0
	v_cvt_pk_bf16_f32 v230, v42, v43
	v_cvt_pk_bf16_f32 v231, v44, v45
	v_cvt_pk_bf16_f32 v232, v46, v47
	v_cvt_pk_bf16_f32 v233, v48, v49
	s_waitcnt lgkmcnt(2)
	s_nop 1
	v_mfma_f32_32x32x16_bf16 v[130:145], v[222:225], v[230:233], v[130:145]
	v_mfma_f32_32x32x16_bf16 v[234:249], v[226:229], v[230:233], v[234:249]
	ds_read2_b64 v[222:225], v178 offset0:28 offset1:30
	ds_read2_b64 v[226:229], v250 offset0:60 offset1:62
	s_nop 0
	v_cvt_pk_bf16_f32 v230, v50, v51
	v_cvt_pk_bf16_f32 v231, v52, v53
	v_cvt_pk_bf16_f32 v232, v54, v55
	v_cvt_pk_bf16_f32 v233, v56, v57
	s_waitcnt lgkmcnt(2)
	s_nop 1
	v_mfma_f32_32x32x16_bf16 v[130:145], v[194:197], v[230:233], v[130:145]
	v_mfma_f32_32x32x16_bf16 v[234:249], v[218:221], v[230:233], v[234:249]
	ds_read2_b64 v[194:197], v178 offset0:32 offset1:34
	ds_read2_b64 v[218:221], v250 offset0:64 offset1:66
	s_nop 0
	v_cvt_pk_bf16_f32 v230, v58, v59
	v_cvt_pk_bf16_f32 v231, v60, v61
	v_cvt_pk_bf16_f32 v232, v62, v63
	v_cvt_pk_bf16_f32 v233, v64, v65
	s_waitcnt lgkmcnt(2)
	s_nop 1
	v_mfma_f32_32x32x16_bf16 v[130:145], v[222:225], v[230:233], v[130:145]
	v_mfma_f32_32x32x16_bf16 v[234:249], v[226:229], v[230:233], v[234:249]
	ds_read2_b64 v[222:225], v178 offset0:36 offset1:38
	ds_read2_b64 v[226:229], v250 offset0:68 offset1:70
	s_nop 0
	v_cvt_pk_bf16_f32 v230, v66, v67
	v_cvt_pk_bf16_f32 v231, v68, v69
	v_cvt_pk_bf16_f32 v232, v70, v71
	v_cvt_pk_bf16_f32 v233, v72, v73
	s_waitcnt lgkmcnt(2)
	s_nop 1
	v_mfma_f32_32x32x16_bf16 v[130:145], v[194:197], v[230:233], v[130:145]
	v_mfma_f32_32x32x16_bf16 v[234:249], v[218:221], v[230:233], v[234:249]
	ds_read2_b64 v[194:197], v178 offset0:40 offset1:42
	ds_read2_b64 v[218:221], v250 offset0:72 offset1:74
	s_nop 0
	v_cvt_pk_bf16_f32 v230, v74, v75
	v_cvt_pk_bf16_f32 v231, v76, v77
	v_cvt_pk_bf16_f32 v232, v78, v79
	v_cvt_pk_bf16_f32 v233, v80, v81
	s_waitcnt lgkmcnt(2)
	s_nop 1
	v_mfma_f32_32x32x16_bf16 v[130:145], v[222:225], v[230:233], v[130:145]
	v_mfma_f32_32x32x16_bf16 v[234:249], v[226:229], v[230:233], v[234:249]
	ds_read2_b64 v[222:225], v178 offset0:44 offset1:46
	ds_read2_b64 v[226:229], v250 offset0:76 offset1:78
	s_nop 0
	v_cvt_pk_bf16_f32 v230, v82, v83
	v_cvt_pk_bf16_f32 v231, v84, v85
	v_cvt_pk_bf16_f32 v232, v86, v87
	v_cvt_pk_bf16_f32 v233, v88, v89
	s_waitcnt lgkmcnt(2)
	s_nop 1
	v_mfma_f32_32x32x16_bf16 v[130:145], v[194:197], v[230:233], v[130:145]
	v_mfma_f32_32x32x16_bf16 v[234:249], v[218:221], v[230:233], v[234:249]
	ds_read2_b64 v[194:197], v178 offset0:48 offset1:50
	ds_read2_b64 v[218:221], v250 offset0:80 offset1:82
	s_nop 0
	v_cvt_pk_bf16_f32 v230, v90, v91
	v_cvt_pk_bf16_f32 v231, v92, v93
	v_cvt_pk_bf16_f32 v232, v94, v95
	v_cvt_pk_bf16_f32 v233, v96, v97
	s_waitcnt lgkmcnt(2)
	s_nop 1
	v_mfma_f32_32x32x16_bf16 v[130:145], v[222:225], v[230:233], v[130:145]
	v_mfma_f32_32x32x16_bf16 v[234:249], v[226:229], v[230:233], v[234:249]
	ds_read2_b64 v[222:225], v178 offset0:52 offset1:54
	ds_read2_b64 v[226:229], v250 offset0:84 offset1:86
	s_nop 0
	v_cvt_pk_bf16_f32 v230, v98, v99
	v_cvt_pk_bf16_f32 v231, v100, v101
	v_cvt_pk_bf16_f32 v232, v102, v103
	v_cvt_pk_bf16_f32 v233, v104, v105
	s_waitcnt lgkmcnt(2)
	s_nop 1
	v_mfma_f32_32x32x16_bf16 v[130:145], v[194:197], v[230:233], v[130:145]
	v_mfma_f32_32x32x16_bf16 v[234:249], v[218:221], v[230:233], v[234:249]
	ds_read2_b64 v[194:197], v178 offset0:56 offset1:58
	ds_read2_b64 v[218:221], v250 offset0:88 offset1:90
	s_nop 0
	v_cvt_pk_bf16_f32 v230, v106, v107
	v_cvt_pk_bf16_f32 v231, v108, v109
	v_cvt_pk_bf16_f32 v232, v110, v111
	v_cvt_pk_bf16_f32 v233, v112, v113
	s_waitcnt lgkmcnt(2)
	s_nop 1
	v_mfma_f32_32x32x16_bf16 v[130:145], v[222:225], v[230:233], v[130:145]
	v_mfma_f32_32x32x16_bf16 v[234:249], v[226:229], v[230:233], v[234:249]
	ds_read2_b64 v[222:225], v178 offset0:60 offset1:62
	ds_read2_b64 v[226:229], v250 offset0:92 offset1:94
	s_nop 0
	v_cvt_pk_bf16_f32 v230, v114, v115
	v_cvt_pk_bf16_f32 v231, v116, v117
	v_cvt_pk_bf16_f32 v232, v118, v119
	v_cvt_pk_bf16_f32 v233, v120, v121
	s_waitcnt lgkmcnt(2)
	s_nop 1
	v_mfma_f32_32x32x16_bf16 v[130:145], v[194:197], v[230:233], v[130:145]
	v_mfma_f32_32x32x16_bf16 v[234:249], v[218:221], v[230:233], v[234:249]
	s_nop 0
	v_cvt_pk_bf16_f32 v230, v122, v123
	v_cvt_pk_bf16_f32 v231, v124, v125
	v_cvt_pk_bf16_f32 v232, v126, v127
	v_cvt_pk_bf16_f32 v233, v128, v129
	s_waitcnt lgkmcnt(0)
	s_nop 1
	v_mfma_f32_32x32x16_bf16 v[130:145], v[222:225], v[230:233], v[130:145]
	v_mfma_f32_32x32x16_bf16 v[234:249], v[226:229], v[230:233], v[234:249]
	v_or_b32_e32 v172, v168, v174
	v_ashrrev_i32_e32 v173, 31, v172
	v_fma_f32 v193, 0, v192, v153
	v_exp_f32_e32 v193, v193
	v_lshlrev_b64 v[172:173], 12, v[172:173]
	v_lshl_add_u64 v[194:195], v[170:171], 0, v[172:173]
	s_nop 7
	v_mul_f32_e32 v130, v193, v130
	v_mov_b32_e32 v251, 0x7fff
	v_bfe_u32 v250, v130, 16, 1
	v_add3_u32 v130, v130, v250, v251
	global_store_short_d16_hi v[194:195], v130, off
	v_add_f32_e32 v130, v153, v192
	v_exp_f32_e32 v130, v130
	s_nop 0
	v_mul_f32_e32 v130, v130, v131
	v_bfe_u32 v250, v130, 16, 1
	v_add3_u32 v193, v130, v250, v251
	v_or_b32_e32 v130, 0x1000, v172
	v_mov_b32_e32 v131, v173
	v_lshl_add_u64 v[130:131], v[170:171], 0, v[130:131]
	global_store_short_d16_hi v[130:131], v193, off
	v_fma_f32 v130, 2.0, v192, v153
	v_exp_f32_e32 v130, v130
	v_mov_b32_e32 v131, v173
	v_mul_f32_e32 v130, v130, v132
	v_bfe_u32 v250, v130, 16, 1
	v_add3_u32 v132, v130, v250, v251
	v_or_b32_e32 v130, 0x2000, v172
	v_lshl_add_u64 v[130:131], v[170:171], 0, v[130:131]
	global_store_short_d16_hi v[130:131], v132, off
	v_fmamk_f32 v130, v192, 0x40400000, v153
	v_exp_f32_e32 v130, v130
	v_mov_b32_e32 v131, v173
	v_mul_f32_e32 v130, v130, v133
	v_bfe_u32 v250, v130, 16, 1
	v_add3_u32 v132, v130, v250, v251
	v_or_b32_e32 v130, 0x3000, v172
	v_lshl_add_u64 v[130:131], v[170:171], 0, v[130:131]
	global_store_short_d16_hi v[130:131], v132, off
	v_fmamk_f32 v130, v192, 0x41000000, v153
	v_exp_f32_e32 v130, v130
	v_mov_b32_e32 v131, v173
	v_mul_f32_e32 v130, v130, v134
	v_bfe_u32 v250, v130, 16, 1
	v_add3_u32 v132, v130, v250, v251
	v_or_b32_e32 v130, 0x8000, v172
	v_lshl_add_u64 v[130:131], v[170:171], 0, v[130:131]
	global_store_short_d16_hi v[130:131], v132, off
	v_fmamk_f32 v130, v192, 0x41100000, v153
	v_exp_f32_e32 v130, v130
	v_mov_b32_e32 v131, v173
	v_mul_f32_e32 v130, v130, v135
	v_bfe_u32 v250, v130, 16, 1
	v_add3_u32 v132, v130, v250, v251
	v_or_b32_e32 v130, 0x9000, v172
	v_lshl_add_u64 v[130:131], v[170:171], 0, v[130:131]
	global_store_short_d16_hi v[130:131], v132, off
	v_fmamk_f32 v130, v192, 0x41200000, v153
	v_exp_f32_e32 v130, v130
	v_mov_b32_e32 v131, v173
	v_mul_f32_e32 v130, v130, v136
	v_bfe_u32 v250, v130, 16, 1
	v_add3_u32 v132, v130, v250, v251
	v_or_b32_e32 v130, 0xa000, v172
	v_lshl_add_u64 v[130:131], v[170:171], 0, v[130:131]
	global_store_short_d16_hi v[130:131], v132, off
	v_fmamk_f32 v130, v192, 0x41300000, v153
	v_exp_f32_e32 v130, v130
	v_mov_b32_e32 v131, v173
	v_mul_f32_e32 v130, v130, v137
	v_bfe_u32 v250, v130, 16, 1
	v_add3_u32 v132, v130, v250, v251
	v_or_b32_e32 v130, 0xb000, v172
	v_lshl_add_u64 v[130:131], v[170:171], 0, v[130:131]
	global_store_short_d16_hi v[130:131], v132, off
	v_fmamk_f32 v130, v192, 0x41800000, v153
	v_exp_f32_e32 v130, v130
	v_mov_b32_e32 v131, v173
	v_mul_f32_e32 v130, v130, v138
	v_bfe_u32 v250, v130, 16, 1
	v_add3_u32 v132, v130, v250, v251
	v_or_b32_e32 v130, 0x10000, v172
	v_lshl_add_u64 v[130:131], v[170:171], 0, v[130:131]
	global_store_short_d16_hi v[130:131], v132, off
	v_fmamk_f32 v130, v192, 0x41880000, v153
	v_exp_f32_e32 v130, v130
	v_mov_b32_e32 v131, v173
	v_mul_f32_e32 v130, v130, v139
	v_bfe_u32 v250, v130, 16, 1
	v_add3_u32 v132, v130, v250, v251
	v_or_b32_e32 v130, 0x11000, v172
	v_lshl_add_u64 v[130:131], v[170:171], 0, v[130:131]
	global_store_short_d16_hi v[130:131], v132, off
	v_fmamk_f32 v130, v192, 0x41900000, v153
	v_exp_f32_e32 v130, v130
	v_mov_b32_e32 v131, v173
	v_mul_f32_e32 v130, v130, v140
	v_bfe_u32 v250, v130, 16, 1
	v_add3_u32 v132, v130, v250, v251
	v_or_b32_e32 v130, 0x12000, v172
	v_lshl_add_u64 v[130:131], v[170:171], 0, v[130:131]
	global_store_short_d16_hi v[130:131], v132, off
	v_fmamk_f32 v130, v192, 0x41980000, v153
	v_exp_f32_e32 v130, v130
	v_mov_b32_e32 v131, v173
	v_mul_f32_e32 v130, v130, v141
	v_bfe_u32 v250, v130, 16, 1
	v_add3_u32 v132, v130, v250, v251
	v_or_b32_e32 v130, 0x13000, v172
	v_lshl_add_u64 v[130:131], v[170:171], 0, v[130:131]
	global_store_short_d16_hi v[130:131], v132, off
	v_fmamk_f32 v130, v192, 0x41c00000, v153
	v_exp_f32_e32 v130, v130
	v_mov_b32_e32 v131, v173
	v_mul_f32_e32 v130, v130, v142
	v_bfe_u32 v250, v130, 16, 1
	v_add3_u32 v132, v130, v250, v251
	v_or_b32_e32 v130, 0x18000, v172
	v_lshl_add_u64 v[130:131], v[170:171], 0, v[130:131]
	global_store_short_d16_hi v[130:131], v132, off
	v_fmamk_f32 v130, v192, 0x41c80000, v153
	v_exp_f32_e32 v130, v130
	v_mov_b32_e32 v131, v173
	v_mul_f32_e32 v130, v130, v143
	v_bfe_u32 v250, v130, 16, 1
	v_add3_u32 v132, v130, v250, v251
	v_or_b32_e32 v130, 0x19000, v172
	v_lshl_add_u64 v[130:131], v[170:171], 0, v[130:131]
	global_store_short_d16_hi v[130:131], v132, off
	v_fmamk_f32 v130, v192, 0x41d00000, v153
	v_exp_f32_e32 v130, v130
	v_mov_b32_e32 v131, v173
	v_mul_f32_e32 v130, v130, v144
	v_bfe_u32 v250, v130, 16, 1
	v_add3_u32 v132, v130, v250, v251
	v_or_b32_e32 v130, 0x1a000, v172
	v_lshl_add_u64 v[130:131], v[170:171], 0, v[130:131]
	global_store_short_d16_hi v[130:131], v132, off
	v_fmamk_f32 v130, v192, 0x41d80000, v153
	v_exp_f32_e32 v130, v130
	v_mov_b32_e32 v131, v173
	v_mul_f32_e32 v130, v130, v145
	v_bfe_u32 v250, v130, 16, 1
	v_add3_u32 v132, v130, v250, v251
	v_or_b32_e32 v130, 0x1b000, v172
	v_lshl_add_u64 v[130:131], v[170:171], 0, v[130:131]
	global_store_short_d16_hi v[130:131], v132, off
	v_mov_b32_e32 v130, v234
	v_mov_b32_e32 v131, v235
	v_mov_b32_e32 v132, v236
	v_mov_b32_e32 v133, v237
	v_mov_b32_e32 v134, v238
	v_mov_b32_e32 v135, v239
	v_mov_b32_e32 v136, v240
	v_mov_b32_e32 v137, v241
	v_mov_b32_e32 v138, v242
	v_mov_b32_e32 v139, v243
	v_mov_b32_e32 v140, v244
	v_mov_b32_e32 v141, v245
	v_mov_b32_e32 v142, v246
	v_mov_b32_e32 v143, v247
	v_mov_b32_e32 v144, v248
	v_mov_b32_e32 v145, v249
	v_fmamk_f32 v193, v192, 0x42000000, v153
	v_exp_f32_e32 v193, v193
	v_or_b32_e32 v194, 0x20000, v172
	v_mov_b32_e32 v195, v173
	v_lshl_add_u64 v[194:195], v[170:171], 0, v[194:195]
	s_nop 6
	v_mul_f32_e32 v130, v193, v130
	v_mov_b32_e32 v251, 0x7fff
	v_bfe_u32 v250, v130, 16, 1
	v_add3_u32 v130, v130, v250, v251
	global_store_short_d16_hi v[194:195], v130, off
	v_fmamk_f32 v130, v192, 0x42040000, v153
	v_exp_f32_e32 v130, v130
	s_nop 0
	v_mul_f32_e32 v130, v130, v131
	v_bfe_u32 v250, v130, 16, 1
	v_add3_u32 v193, v130, v250, v251
	v_or_b32_e32 v130, 0x21000, v172
	v_mov_b32_e32 v131, v173
	v_lshl_add_u64 v[130:131], v[170:171], 0, v[130:131]
	global_store_short_d16_hi v[130:131], v193, off
	v_fmamk_f32 v130, v192, 0x42080000, v153
	v_exp_f32_e32 v130, v130
	v_mov_b32_e32 v131, v173
	v_mul_f32_e32 v130, v130, v132
	v_bfe_u32 v250, v130, 16, 1
	v_add3_u32 v132, v130, v250, v251
	v_or_b32_e32 v130, 0x22000, v172
	v_lshl_add_u64 v[130:131], v[170:171], 0, v[130:131]
	global_store_short_d16_hi v[130:131], v132, off
	v_fmamk_f32 v130, v192, 0x420c0000, v153
	v_exp_f32_e32 v130, v130
	v_mov_b32_e32 v131, v173
	v_mul_f32_e32 v130, v130, v133
	v_bfe_u32 v250, v130, 16, 1
	v_add3_u32 v132, v130, v250, v251
	v_or_b32_e32 v130, 0x23000, v172
	v_lshl_add_u64 v[130:131], v[170:171], 0, v[130:131]
	global_store_short_d16_hi v[130:131], v132, off
	v_fmamk_f32 v130, v192, 0x42200000, v153
	v_exp_f32_e32 v130, v130
	v_mov_b32_e32 v131, v173
	v_mul_f32_e32 v130, v130, v134
	v_bfe_u32 v250, v130, 16, 1
	v_add3_u32 v132, v130, v250, v251
	v_or_b32_e32 v130, 0x28000, v172
	v_lshl_add_u64 v[130:131], v[170:171], 0, v[130:131]
	global_store_short_d16_hi v[130:131], v132, off
	v_fmamk_f32 v130, v192, 0x42240000, v153
	v_exp_f32_e32 v130, v130
	v_mov_b32_e32 v131, v173
	v_mul_f32_e32 v130, v130, v135
	v_bfe_u32 v250, v130, 16, 1
	v_add3_u32 v132, v130, v250, v251
	v_or_b32_e32 v130, 0x29000, v172
	v_lshl_add_u64 v[130:131], v[170:171], 0, v[130:131]
	global_store_short_d16_hi v[130:131], v132, off
	v_fmamk_f32 v130, v192, 0x42280000, v153
	v_exp_f32_e32 v130, v130
	v_mov_b32_e32 v131, v173
	v_mul_f32_e32 v130, v130, v136
	v_bfe_u32 v250, v130, 16, 1
	v_add3_u32 v132, v130, v250, v251
	v_or_b32_e32 v130, 0x2a000, v172
	v_lshl_add_u64 v[130:131], v[170:171], 0, v[130:131]
	global_store_short_d16_hi v[130:131], v132, off
	v_fmamk_f32 v130, v192, 0x422c0000, v153
	v_exp_f32_e32 v130, v130
	v_mov_b32_e32 v131, v173
	v_mul_f32_e32 v130, v130, v137
	v_bfe_u32 v250, v130, 16, 1
	v_add3_u32 v132, v130, v250, v251
	v_or_b32_e32 v130, 0x2b000, v172
	v_lshl_add_u64 v[130:131], v[170:171], 0, v[130:131]
	global_store_short_d16_hi v[130:131], v132, off
	v_fmamk_f32 v130, v192, 0x42400000, v153
	v_exp_f32_e32 v130, v130
	v_mov_b32_e32 v131, v173
	v_mul_f32_e32 v130, v130, v138
	v_bfe_u32 v250, v130, 16, 1
	v_add3_u32 v132, v130, v250, v251
	v_or_b32_e32 v130, 0x30000, v172
	v_lshl_add_u64 v[130:131], v[170:171], 0, v[130:131]
	global_store_short_d16_hi v[130:131], v132, off
	v_fmamk_f32 v130, v192, 0x42440000, v153
	v_exp_f32_e32 v130, v130
	v_mov_b32_e32 v131, v173
	v_mul_f32_e32 v130, v130, v139
	v_bfe_u32 v250, v130, 16, 1
	v_add3_u32 v132, v130, v250, v251
	v_or_b32_e32 v130, 0x31000, v172
	v_lshl_add_u64 v[130:131], v[170:171], 0, v[130:131]
	global_store_short_d16_hi v[130:131], v132, off
	v_fmamk_f32 v130, v192, 0x42480000, v153
	v_exp_f32_e32 v130, v130
	v_mov_b32_e32 v131, v173
	v_mul_f32_e32 v130, v130, v140
	v_bfe_u32 v250, v130, 16, 1
	v_add3_u32 v132, v130, v250, v251
	v_or_b32_e32 v130, 0x32000, v172
	v_lshl_add_u64 v[130:131], v[170:171], 0, v[130:131]
	global_store_short_d16_hi v[130:131], v132, off
	v_fmamk_f32 v130, v192, 0x424c0000, v153
	v_exp_f32_e32 v130, v130
	v_mov_b32_e32 v131, v173
	v_mul_f32_e32 v130, v130, v141
	v_bfe_u32 v250, v130, 16, 1
	v_add3_u32 v132, v130, v250, v251
	v_or_b32_e32 v130, 0x33000, v172
	v_lshl_add_u64 v[130:131], v[170:171], 0, v[130:131]
	global_store_short_d16_hi v[130:131], v132, off
	v_fmamk_f32 v130, v192, 0x42600000, v153
	v_exp_f32_e32 v130, v130
	v_mov_b32_e32 v131, v173
	v_mul_f32_e32 v130, v130, v142
	v_bfe_u32 v250, v130, 16, 1
	v_add3_u32 v132, v130, v250, v251
	v_or_b32_e32 v130, 0x38000, v172
	v_lshl_add_u64 v[130:131], v[170:171], 0, v[130:131]
	global_store_short_d16_hi v[130:131], v132, off
	v_fmamk_f32 v130, v192, 0x42640000, v153
	v_exp_f32_e32 v130, v130
	v_mov_b32_e32 v131, v173
	v_mul_f32_e32 v130, v130, v143
	v_bfe_u32 v250, v130, 16, 1
	v_add3_u32 v132, v130, v250, v251
	v_or_b32_e32 v130, 0x39000, v172
	v_lshl_add_u64 v[130:131], v[170:171], 0, v[130:131]
	global_store_short_d16_hi v[130:131], v132, off
	v_fmamk_f32 v130, v192, 0x42680000, v153
	v_exp_f32_e32 v130, v130
	v_mov_b32_e32 v131, v173
	v_mul_f32_e32 v130, v130, v144
	v_bfe_u32 v250, v130, 16, 1
	v_add3_u32 v132, v130, v250, v251
	v_or_b32_e32 v130, 0x3a000, v172
	v_lshl_add_u64 v[130:131], v[170:171], 0, v[130:131]
	global_store_short_d16_hi v[130:131], v132, off
	v_fmamk_f32 v130, v192, 0x426c0000, v153
	v_exp_f32_e32 v130, v130
	v_mov_b32_e32 v131, v173
	v_mul_f32_e32 v130, v130, v145
	v_bfe_u32 v250, v130, 16, 1
	v_add3_u32 v132, v130, v250, v251
	v_or_b32_e32 v130, 0x3b000, v172
	v_lshl_add_u64 v[130:131], v[170:171], 0, v[130:131]
	global_store_short_d16_hi v[130:131], v132, off
	v_add_u32_e32 v250, 0xc000, v178
	v_add_u32_e32 v251, 0x8000, v178
	ds_read2_b64 v[194:197], v251 offset0:64 offset1:66
	ds_read2_b64 v[218:221], v250 offset0:96 offset1:98
	ds_read2_b64 v[222:225], v251 offset0:68 offset1:70
	ds_read2_b64 v[226:229], v250 offset0:100 offset1:102
	s_nop 0
	v_cvt_pk_bf16_f32 v230, v2, v3
	v_cvt_pk_bf16_f32 v231, v4, v5
	v_cvt_pk_bf16_f32 v232, v6, v7
	v_cvt_pk_bf16_f32 v233, v8, v9
	s_waitcnt lgkmcnt(2)
	s_nop 1
	v_mfma_f32_32x32x16_bf16 v[130:145], v[194:197], v[230:233], 0
	v_mfma_f32_32x32x16_bf16 v[234:249], v[218:221], v[230:233], 0
	ds_read2_b64 v[194:197], v251 offset0:72 offset1:74
	ds_read2_b64 v[218:221], v250 offset0:104 offset1:106
	s_nop 0
	v_cvt_pk_bf16_f32 v230, v10, v11
	v_cvt_pk_bf16_f32 v231, v12, v13
	v_cvt_pk_bf16_f32 v232, v14, v15
	v_cvt_pk_bf16_f32 v233, v16, v17
	s_waitcnt lgkmcnt(2)
	s_nop 1
	v_mfma_f32_32x32x16_bf16 v[130:145], v[222:225], v[230:233], v[130:145]
	v_mfma_f32_32x32x16_bf16 v[234:249], v[226:229], v[230:233], v[234:249]
	ds_read2_b64 v[222:225], v251 offset0:76 offset1:78
	ds_read2_b64 v[226:229], v250 offset0:108 offset1:110
	s_nop 0
	v_cvt_pk_bf16_f32 v230, v18, v19
	v_cvt_pk_bf16_f32 v231, v20, v21
	v_cvt_pk_bf16_f32 v232, v22, v23
	v_cvt_pk_bf16_f32 v233, v24, v25
	s_waitcnt lgkmcnt(2)
	s_nop 1
	v_mfma_f32_32x32x16_bf16 v[130:145], v[194:197], v[230:233], v[130:145]
	v_mfma_f32_32x32x16_bf16 v[234:249], v[218:221], v[230:233], v[234:249]
	ds_read2_b64 v[194:197], v251 offset0:80 offset1:82
	ds_read2_b64 v[218:221], v250 offset0:112 offset1:114
	s_nop 0
	v_cvt_pk_bf16_f32 v230, v26, v27
	v_cvt_pk_bf16_f32 v231, v28, v29
	v_cvt_pk_bf16_f32 v232, v30, v31
	v_cvt_pk_bf16_f32 v233, v32, v33
	s_waitcnt lgkmcnt(2)
	s_nop 1
	v_mfma_f32_32x32x16_bf16 v[130:145], v[222:225], v[230:233], v[130:145]
	v_mfma_f32_32x32x16_bf16 v[234:249], v[226:229], v[230:233], v[234:249]
	ds_read2_b64 v[222:225], v251 offset0:84 offset1:86
	ds_read2_b64 v[226:229], v250 offset0:116 offset1:118
	s_nop 0
	v_cvt_pk_bf16_f32 v230, v34, v35
	v_cvt_pk_bf16_f32 v231, v36, v37
	v_cvt_pk_bf16_f32 v232, v38, v39
	v_cvt_pk_bf16_f32 v233, v40, v41
	s_waitcnt lgkmcnt(2)
	s_nop 1
	v_mfma_f32_32x32x16_bf16 v[130:145], v[194:197], v[230:233], v[130:145]
	v_mfma_f32_32x32x16_bf16 v[234:249], v[218:221], v[230:233], v[234:249]
	ds_read2_b64 v[194:197], v251 offset0:88 offset1:90
	ds_read2_b64 v[218:221], v250 offset0:120 offset1:122
	s_nop 0
	v_cvt_pk_bf16_f32 v230, v42, v43
	v_cvt_pk_bf16_f32 v231, v44, v45
	v_cvt_pk_bf16_f32 v232, v46, v47
	v_cvt_pk_bf16_f32 v233, v48, v49
	s_waitcnt lgkmcnt(2)
	s_nop 1
	v_mfma_f32_32x32x16_bf16 v[130:145], v[222:225], v[230:233], v[130:145]
	v_mfma_f32_32x32x16_bf16 v[234:249], v[226:229], v[230:233], v[234:249]
	ds_read2_b64 v[222:225], v251 offset0:92 offset1:94
	ds_read2_b64 v[226:229], v250 offset0:124 offset1:126
	s_nop 0
	v_cvt_pk_bf16_f32 v230, v50, v51
	v_cvt_pk_bf16_f32 v231, v52, v53
	v_cvt_pk_bf16_f32 v232, v54, v55
	v_cvt_pk_bf16_f32 v233, v56, v57
	s_waitcnt lgkmcnt(2)
	s_nop 1
	v_mfma_f32_32x32x16_bf16 v[130:145], v[194:197], v[230:233], v[130:145]
	v_mfma_f32_32x32x16_bf16 v[234:249], v[218:221], v[230:233], v[234:249]
	ds_read2_b64 v[194:197], v251 offset0:96 offset1:98
	ds_read2_b64 v[218:221], v250 offset0:128 offset1:130
	s_nop 0
	v_cvt_pk_bf16_f32 v230, v58, v59
	v_cvt_pk_bf16_f32 v231, v60, v61
	v_cvt_pk_bf16_f32 v232, v62, v63
	v_cvt_pk_bf16_f32 v233, v64, v65
	s_waitcnt lgkmcnt(2)
	s_nop 1
	v_mfma_f32_32x32x16_bf16 v[130:145], v[222:225], v[230:233], v[130:145]
	v_mfma_f32_32x32x16_bf16 v[234:249], v[226:229], v[230:233], v[234:249]
	ds_read2_b64 v[222:225], v251 offset0:100 offset1:102
	ds_read2_b64 v[226:229], v250 offset0:132 offset1:134
	s_nop 0
	v_cvt_pk_bf16_f32 v230, v66, v67
	v_cvt_pk_bf16_f32 v231, v68, v69
	v_cvt_pk_bf16_f32 v232, v70, v71
	v_cvt_pk_bf16_f32 v233, v72, v73
	s_waitcnt lgkmcnt(2)
	s_nop 1
	v_mfma_f32_32x32x16_bf16 v[130:145], v[194:197], v[230:233], v[130:145]
	v_mfma_f32_32x32x16_bf16 v[234:249], v[218:221], v[230:233], v[234:249]
	ds_read2_b64 v[194:197], v251 offset0:104 offset1:106
	ds_read2_b64 v[218:221], v250 offset0:136 offset1:138
	s_nop 0
	v_cvt_pk_bf16_f32 v230, v74, v75
	v_cvt_pk_bf16_f32 v231, v76, v77
	v_cvt_pk_bf16_f32 v232, v78, v79
	v_cvt_pk_bf16_f32 v233, v80, v81
	s_waitcnt lgkmcnt(2)
	s_nop 1
	v_mfma_f32_32x32x16_bf16 v[130:145], v[222:225], v[230:233], v[130:145]
	v_mfma_f32_32x32x16_bf16 v[234:249], v[226:229], v[230:233], v[234:249]
	ds_read2_b64 v[222:225], v251 offset0:108 offset1:110
	ds_read2_b64 v[226:229], v250 offset0:140 offset1:142
	s_nop 0
	v_cvt_pk_bf16_f32 v230, v82, v83
	v_cvt_pk_bf16_f32 v231, v84, v85
	v_cvt_pk_bf16_f32 v232, v86, v87
	v_cvt_pk_bf16_f32 v233, v88, v89
	s_waitcnt lgkmcnt(2)
	s_nop 1
	v_mfma_f32_32x32x16_bf16 v[130:145], v[194:197], v[230:233], v[130:145]
	v_mfma_f32_32x32x16_bf16 v[234:249], v[218:221], v[230:233], v[234:249]
	ds_read2_b64 v[194:197], v251 offset0:112 offset1:114
	ds_read2_b64 v[218:221], v250 offset0:144 offset1:146
	s_nop 0
	v_cvt_pk_bf16_f32 v230, v90, v91
	v_cvt_pk_bf16_f32 v231, v92, v93
	v_cvt_pk_bf16_f32 v232, v94, v95
	v_cvt_pk_bf16_f32 v233, v96, v97
	s_waitcnt lgkmcnt(2)
	s_nop 1
	v_mfma_f32_32x32x16_bf16 v[130:145], v[222:225], v[230:233], v[130:145]
	v_mfma_f32_32x32x16_bf16 v[234:249], v[226:229], v[230:233], v[234:249]
	ds_read2_b64 v[222:225], v251 offset0:116 offset1:118
	ds_read2_b64 v[226:229], v250 offset0:148 offset1:150
	s_nop 0
	v_cvt_pk_bf16_f32 v230, v98, v99
	v_cvt_pk_bf16_f32 v231, v100, v101
	v_cvt_pk_bf16_f32 v232, v102, v103
	v_cvt_pk_bf16_f32 v233, v104, v105
	s_waitcnt lgkmcnt(2)
	s_nop 1
	v_mfma_f32_32x32x16_bf16 v[130:145], v[194:197], v[230:233], v[130:145]
	v_mfma_f32_32x32x16_bf16 v[234:249], v[218:221], v[230:233], v[234:249]
	ds_read2_b64 v[194:197], v251 offset0:120 offset1:122
	ds_read2_b64 v[218:221], v250 offset0:152 offset1:154
	s_nop 0
	v_cvt_pk_bf16_f32 v230, v106, v107
	v_cvt_pk_bf16_f32 v231, v108, v109
	v_cvt_pk_bf16_f32 v232, v110, v111
	v_cvt_pk_bf16_f32 v233, v112, v113
	s_waitcnt lgkmcnt(2)
	s_nop 1
	v_mfma_f32_32x32x16_bf16 v[130:145], v[222:225], v[230:233], v[130:145]
	v_mfma_f32_32x32x16_bf16 v[234:249], v[226:229], v[230:233], v[234:249]
	ds_read2_b64 v[222:225], v251 offset0:124 offset1:126
	ds_read2_b64 v[226:229], v250 offset0:156 offset1:158
	s_nop 0
	v_cvt_pk_bf16_f32 v230, v114, v115
	v_cvt_pk_bf16_f32 v231, v116, v117
	v_cvt_pk_bf16_f32 v232, v118, v119
	v_cvt_pk_bf16_f32 v233, v120, v121
	s_waitcnt lgkmcnt(2)
	s_nop 1
	v_mfma_f32_32x32x16_bf16 v[130:145], v[194:197], v[230:233], v[130:145]
	v_mfma_f32_32x32x16_bf16 v[234:249], v[218:221], v[230:233], v[234:249]
	s_nop 0
	v_cvt_pk_bf16_f32 v230, v122, v123
	v_cvt_pk_bf16_f32 v231, v124, v125
	v_cvt_pk_bf16_f32 v232, v126, v127
	v_cvt_pk_bf16_f32 v233, v128, v129
	s_waitcnt lgkmcnt(0)
	s_nop 1
	v_mfma_f32_32x32x16_bf16 v[130:145], v[222:225], v[230:233], v[130:145]
	v_mfma_f32_32x32x16_bf16 v[234:249], v[226:229], v[230:233], v[234:249]
	v_fmamk_f32 v193, v192, 0x42800000, v153
	v_exp_f32_e32 v193, v193
	v_or_b32_e32 v194, 0x40000, v172
	v_mov_b32_e32 v195, v173
	v_lshl_add_u64 v[194:195], v[170:171], 0, v[194:195]
	s_nop 6
	v_mul_f32_e32 v130, v193, v130
	v_mov_b32_e32 v251, 0x7fff
	v_bfe_u32 v250, v130, 16, 1
	v_add3_u32 v130, v130, v250, v251
	global_store_short_d16_hi v[194:195], v130, off
	v_fmamk_f32 v130, v192, 0x42820000, v153
	v_exp_f32_e32 v130, v130
	s_nop 0
	v_mul_f32_e32 v130, v130, v131
	v_bfe_u32 v250, v130, 16, 1
	v_add3_u32 v193, v130, v250, v251
	v_or_b32_e32 v130, 0x41000, v172
	v_mov_b32_e32 v131, v173
	v_lshl_add_u64 v[130:131], v[170:171], 0, v[130:131]
	global_store_short_d16_hi v[130:131], v193, off
	v_fmamk_f32 v130, v192, 0x42840000, v153
	v_exp_f32_e32 v130, v130
	v_mov_b32_e32 v131, v173
	v_mul_f32_e32 v130, v130, v132
	v_bfe_u32 v250, v130, 16, 1
	v_add3_u32 v132, v130, v250, v251
	v_or_b32_e32 v130, 0x42000, v172
	v_lshl_add_u64 v[130:131], v[170:171], 0, v[130:131]
	global_store_short_d16_hi v[130:131], v132, off
	v_fmamk_f32 v130, v192, 0x42860000, v153
	v_exp_f32_e32 v130, v130
	v_mov_b32_e32 v131, v173
	v_mul_f32_e32 v130, v130, v133
	v_bfe_u32 v250, v130, 16, 1
	v_add3_u32 v132, v130, v250, v251
	v_or_b32_e32 v130, 0x43000, v172
	v_lshl_add_u64 v[130:131], v[170:171], 0, v[130:131]
	global_store_short_d16_hi v[130:131], v132, off
	v_fmamk_f32 v130, v192, 0x42900000, v153
	v_exp_f32_e32 v130, v130
	v_mov_b32_e32 v131, v173
	v_mul_f32_e32 v130, v130, v134
	v_bfe_u32 v250, v130, 16, 1
	v_add3_u32 v132, v130, v250, v251
	v_or_b32_e32 v130, 0x48000, v172
	v_lshl_add_u64 v[130:131], v[170:171], 0, v[130:131]
	global_store_short_d16_hi v[130:131], v132, off
	v_fmamk_f32 v130, v192, 0x42920000, v153
	v_exp_f32_e32 v130, v130
	v_mov_b32_e32 v131, v173
	v_mul_f32_e32 v130, v130, v135
	v_bfe_u32 v250, v130, 16, 1
	v_add3_u32 v132, v130, v250, v251
	v_or_b32_e32 v130, 0x49000, v172
	v_lshl_add_u64 v[130:131], v[170:171], 0, v[130:131]
	global_store_short_d16_hi v[130:131], v132, off
	v_fmamk_f32 v130, v192, 0x42940000, v153
	v_exp_f32_e32 v130, v130
	v_mov_b32_e32 v131, v173
	v_mul_f32_e32 v130, v130, v136
	v_bfe_u32 v250, v130, 16, 1
	v_add3_u32 v132, v130, v250, v251
	v_or_b32_e32 v130, 0x4a000, v172
	v_lshl_add_u64 v[130:131], v[170:171], 0, v[130:131]
	global_store_short_d16_hi v[130:131], v132, off
	v_fmamk_f32 v130, v192, 0x42960000, v153
	v_exp_f32_e32 v130, v130
	v_mov_b32_e32 v131, v173
	v_mul_f32_e32 v130, v130, v137
	v_bfe_u32 v250, v130, 16, 1
	v_add3_u32 v132, v130, v250, v251
	v_or_b32_e32 v130, 0x4b000, v172
	v_lshl_add_u64 v[130:131], v[170:171], 0, v[130:131]
	global_store_short_d16_hi v[130:131], v132, off
	v_fmamk_f32 v130, v192, 0x42a00000, v153
	v_exp_f32_e32 v130, v130
	v_mov_b32_e32 v131, v173
	v_mul_f32_e32 v130, v130, v138
	v_bfe_u32 v250, v130, 16, 1
	v_add3_u32 v132, v130, v250, v251
	v_or_b32_e32 v130, 0x50000, v172
	v_lshl_add_u64 v[130:131], v[170:171], 0, v[130:131]
	global_store_short_d16_hi v[130:131], v132, off
	v_fmamk_f32 v130, v192, 0x42a20000, v153
	v_exp_f32_e32 v130, v130
	v_mov_b32_e32 v131, v173
	v_mul_f32_e32 v130, v130, v139
	v_bfe_u32 v250, v130, 16, 1
	v_add3_u32 v132, v130, v250, v251
	v_or_b32_e32 v130, 0x51000, v172
	v_lshl_add_u64 v[130:131], v[170:171], 0, v[130:131]
	global_store_short_d16_hi v[130:131], v132, off
	v_fmamk_f32 v130, v192, 0x42a40000, v153
	v_exp_f32_e32 v130, v130
	v_mov_b32_e32 v131, v173
	v_mul_f32_e32 v130, v130, v140
	v_bfe_u32 v250, v130, 16, 1
	v_add3_u32 v132, v130, v250, v251
	v_or_b32_e32 v130, 0x52000, v172
	v_lshl_add_u64 v[130:131], v[170:171], 0, v[130:131]
	global_store_short_d16_hi v[130:131], v132, off
	v_fmamk_f32 v130, v192, 0x42a60000, v153
	v_exp_f32_e32 v130, v130
	v_mov_b32_e32 v131, v173
	v_mul_f32_e32 v130, v130, v141
	v_bfe_u32 v250, v130, 16, 1
	v_add3_u32 v132, v130, v250, v251
	v_or_b32_e32 v130, 0x53000, v172
	v_lshl_add_u64 v[130:131], v[170:171], 0, v[130:131]
	global_store_short_d16_hi v[130:131], v132, off
	v_fmamk_f32 v130, v192, 0x42b00000, v153
	v_exp_f32_e32 v130, v130
	v_mov_b32_e32 v131, v173
	v_mul_f32_e32 v130, v130, v142
	v_bfe_u32 v250, v130, 16, 1
	v_add3_u32 v132, v130, v250, v251
	v_or_b32_e32 v130, 0x58000, v172
	v_lshl_add_u64 v[130:131], v[170:171], 0, v[130:131]
	global_store_short_d16_hi v[130:131], v132, off
	v_fmamk_f32 v130, v192, 0x42b20000, v153
	v_exp_f32_e32 v130, v130
	v_mov_b32_e32 v131, v173
	v_mul_f32_e32 v130, v130, v143
	v_bfe_u32 v250, v130, 16, 1
	v_add3_u32 v132, v130, v250, v251
	v_or_b32_e32 v130, 0x59000, v172
	v_lshl_add_u64 v[130:131], v[170:171], 0, v[130:131]
	global_store_short_d16_hi v[130:131], v132, off
	v_fmamk_f32 v130, v192, 0x42b40000, v153
	v_exp_f32_e32 v130, v130
	v_mov_b32_e32 v131, v173
	v_mul_f32_e32 v130, v130, v144
	v_bfe_u32 v250, v130, 16, 1
	v_add3_u32 v132, v130, v250, v251
	v_or_b32_e32 v130, 0x5a000, v172
	v_lshl_add_u64 v[130:131], v[170:171], 0, v[130:131]
	global_store_short_d16_hi v[130:131], v132, off
	v_fmamk_f32 v130, v192, 0x42b60000, v153
	v_exp_f32_e32 v130, v130
	v_mov_b32_e32 v131, v173
	v_mul_f32_e32 v130, v130, v145
	v_bfe_u32 v250, v130, 16, 1
	v_add3_u32 v132, v130, v250, v251
	v_or_b32_e32 v130, 0x5b000, v172
	v_lshl_add_u64 v[130:131], v[170:171], 0, v[130:131]
	global_store_short_d16_hi v[130:131], v132, off
	v_mov_b32_e32 v130, v234
	v_mov_b32_e32 v131, v235
	v_mov_b32_e32 v132, v236
	v_mov_b32_e32 v133, v237
	v_mov_b32_e32 v134, v238
	v_mov_b32_e32 v135, v239
	v_mov_b32_e32 v136, v240
	v_mov_b32_e32 v137, v241
	v_mov_b32_e32 v138, v242
	v_mov_b32_e32 v139, v243
	v_mov_b32_e32 v140, v244
	v_mov_b32_e32 v141, v245
	v_mov_b32_e32 v142, v246
	v_mov_b32_e32 v143, v247
	v_mov_b32_e32 v144, v248
	v_mov_b32_e32 v145, v249
	v_fmamk_f32 v193, v192, 0x42c00000, v153
	v_exp_f32_e32 v193, v193
	v_or_b32_e32 v194, 0x60000, v172
	v_mov_b32_e32 v195, v173
	v_lshl_add_u64 v[194:195], v[170:171], 0, v[194:195]
	s_nop 6
	v_mul_f32_e32 v130, v193, v130
	v_mov_b32_e32 v251, 0x7fff
	v_bfe_u32 v250, v130, 16, 1
	v_add3_u32 v130, v130, v250, v251
	global_store_short_d16_hi v[194:195], v130, off
	v_fmamk_f32 v130, v192, 0x42c20000, v153
	v_exp_f32_e32 v130, v130
	s_nop 0
	v_mul_f32_e32 v130, v130, v131
	v_bfe_u32 v250, v130, 16, 1
	v_add3_u32 v193, v130, v250, v251
	v_or_b32_e32 v130, 0x61000, v172
	v_mov_b32_e32 v131, v173
	v_lshl_add_u64 v[130:131], v[170:171], 0, v[130:131]
	global_store_short_d16_hi v[130:131], v193, off
	v_fmamk_f32 v130, v192, 0x42c40000, v153
	v_exp_f32_e32 v130, v130
	v_mov_b32_e32 v131, v173
	v_mul_f32_e32 v130, v130, v132
	v_bfe_u32 v250, v130, 16, 1
	v_add3_u32 v132, v130, v250, v251
	v_or_b32_e32 v130, 0x62000, v172
	v_lshl_add_u64 v[130:131], v[170:171], 0, v[130:131]
	global_store_short_d16_hi v[130:131], v132, off
	v_fmamk_f32 v130, v192, 0x42c60000, v153
	v_exp_f32_e32 v130, v130
	v_mov_b32_e32 v131, v173
	v_mul_f32_e32 v130, v130, v133
	v_bfe_u32 v250, v130, 16, 1
	v_add3_u32 v132, v130, v250, v251
	v_or_b32_e32 v130, 0x63000, v172
	v_lshl_add_u64 v[130:131], v[170:171], 0, v[130:131]
	global_store_short_d16_hi v[130:131], v132, off
	v_fmamk_f32 v130, v192, 0x42d00000, v153
	v_exp_f32_e32 v130, v130
	v_mov_b32_e32 v131, v173
	v_mul_f32_e32 v130, v130, v134
	v_bfe_u32 v250, v130, 16, 1
	v_add3_u32 v132, v130, v250, v251
	v_or_b32_e32 v130, 0x68000, v172
	v_lshl_add_u64 v[130:131], v[170:171], 0, v[130:131]
	global_store_short_d16_hi v[130:131], v132, off
	v_fmamk_f32 v130, v192, 0x42d20000, v153
	v_exp_f32_e32 v130, v130
	v_mov_b32_e32 v131, v173
	v_mul_f32_e32 v130, v130, v135
	v_bfe_u32 v250, v130, 16, 1
	v_add3_u32 v132, v130, v250, v251
	v_or_b32_e32 v130, 0x69000, v172
	v_lshl_add_u64 v[130:131], v[170:171], 0, v[130:131]
	global_store_short_d16_hi v[130:131], v132, off
	v_fmamk_f32 v130, v192, 0x42d40000, v153
	v_exp_f32_e32 v130, v130
	v_mov_b32_e32 v131, v173
	v_mul_f32_e32 v130, v130, v136
	v_bfe_u32 v250, v130, 16, 1
	v_add3_u32 v132, v130, v250, v251
	v_or_b32_e32 v130, 0x6a000, v172
	v_lshl_add_u64 v[130:131], v[170:171], 0, v[130:131]
	global_store_short_d16_hi v[130:131], v132, off
	v_fmamk_f32 v130, v192, 0x42d60000, v153
	v_exp_f32_e32 v130, v130
	v_mov_b32_e32 v131, v173
	v_mul_f32_e32 v130, v130, v137
	v_bfe_u32 v250, v130, 16, 1
	v_add3_u32 v132, v130, v250, v251
	v_or_b32_e32 v130, 0x6b000, v172
	v_lshl_add_u64 v[130:131], v[170:171], 0, v[130:131]
	global_store_short_d16_hi v[130:131], v132, off
	v_fmamk_f32 v130, v192, 0x42e00000, v153
	v_exp_f32_e32 v130, v130
	v_mov_b32_e32 v131, v173
	v_mul_f32_e32 v130, v130, v138
	v_bfe_u32 v250, v130, 16, 1
	v_add3_u32 v132, v130, v250, v251
	v_or_b32_e32 v130, 0x70000, v172
	v_lshl_add_u64 v[130:131], v[170:171], 0, v[130:131]
	global_store_short_d16_hi v[130:131], v132, off
	v_fmamk_f32 v130, v192, 0x42e20000, v153
	v_exp_f32_e32 v130, v130
	v_mov_b32_e32 v131, v173
	v_mul_f32_e32 v130, v130, v139
	v_bfe_u32 v250, v130, 16, 1
	v_add3_u32 v132, v130, v250, v251
	v_or_b32_e32 v130, 0x71000, v172
	v_lshl_add_u64 v[130:131], v[170:171], 0, v[130:131]
	global_store_short_d16_hi v[130:131], v132, off
	v_fmamk_f32 v130, v192, 0x42e40000, v153
	v_exp_f32_e32 v130, v130
	v_mov_b32_e32 v131, v173
	v_mul_f32_e32 v130, v130, v140
	v_bfe_u32 v250, v130, 16, 1
	v_add3_u32 v132, v130, v250, v251
	v_or_b32_e32 v130, 0x72000, v172
	v_lshl_add_u64 v[130:131], v[170:171], 0, v[130:131]
	global_store_short_d16_hi v[130:131], v132, off
	v_fmamk_f32 v130, v192, 0x42e60000, v153
	v_exp_f32_e32 v130, v130
	v_mov_b32_e32 v131, v173
	v_mul_f32_e32 v130, v130, v141
	v_bfe_u32 v250, v130, 16, 1
	v_add3_u32 v132, v130, v250, v251
	v_or_b32_e32 v130, 0x73000, v172
	v_lshl_add_u64 v[130:131], v[170:171], 0, v[130:131]
	global_store_short_d16_hi v[130:131], v132, off
	v_fmamk_f32 v130, v192, 0x42f00000, v153
	v_exp_f32_e32 v130, v130
	v_mov_b32_e32 v131, v173
	v_mul_f32_e32 v130, v130, v142
	v_bfe_u32 v250, v130, 16, 1
	v_add3_u32 v132, v130, v250, v251
	v_or_b32_e32 v130, 0x78000, v172
	v_lshl_add_u64 v[130:131], v[170:171], 0, v[130:131]
	global_store_short_d16_hi v[130:131], v132, off
	v_fmamk_f32 v130, v192, 0x42f20000, v153
	v_exp_f32_e32 v130, v130
	v_mov_b32_e32 v131, v173
	v_mul_f32_e32 v130, v130, v143
	v_bfe_u32 v250, v130, 16, 1
	v_add3_u32 v132, v130, v250, v251
	v_or_b32_e32 v130, 0x79000, v172
	v_lshl_add_u64 v[130:131], v[170:171], 0, v[130:131]
	global_store_short_d16_hi v[130:131], v132, off
	v_fmamk_f32 v130, v192, 0x42f40000, v153
	v_exp_f32_e32 v130, v130
	v_mov_b32_e32 v131, v173
	v_fmac_f32_e32 v153, 0x42f60000, v192
	v_mul_f32_e32 v130, v130, v144
	v_bfe_u32 v250, v130, 16, 1
	v_add3_u32 v132, v130, v250, v251
	v_or_b32_e32 v130, 0x7a000, v172
	v_lshl_add_u64 v[130:131], v[170:171], 0, v[130:131]
	global_store_short_d16_hi v[130:131], v132, off
	v_exp_f32_e32 v130, v153
	v_or_b32_e32 v172, 0x7b000, v172
	v_mul_f32_e32 v130, v130, v145
	v_bfe_u32 v250, v130, 16, 1
	v_add3_u32 v132, v130, v250, v251
	v_lshl_add_u64 v[130:131], v[170:171], 0, v[172:173]
	global_store_short_d16_hi v[130:131], v132, off
	v_mov_b32_e32 v153, v189
	s_waitcnt vmcnt(63) expcnt(7) lgkmcnt(15)
	s_barrier
	v_lshl_add_u64 v[132:133], s[64:65], 0, v[164:165]
	v_lshlrev_b64 v[130:131], 1, v[168:169]
	v_lshlrev_b64 v[226:227], 14, v[166:167]
	v_lshl_add_u64 v[226:227], s[64:65], 0, v[226:227]
	v_lshl_add_u64 v[226:227], v[226:227], 0, v[130:131]
	v_mov_b32_e32 v228, v152
	v_mov_b32_e32 v229, v1
	v_lshl_add_u64 v[226:227], v[226:227], 0, v[228:229]
	s_mov_b64 s[6:7], 0xf640000
	v_lshl_add_u64 v[226:227], v[226:227], 0, s[6:7]
	global_load_dwordx4 v[234:237], v[226:227], off
	global_load_dwordx4 v[238:241], v[226:227], off offset:32
	global_load_dwordx4 v[242:245], v[226:227], off offset:64
	global_load_dwordx4 v[246:249], v[226:227], off offset:96
	v_lshl_add_u64 v[132:133], v[132:133], 0, v[130:131]
	v_lshlrev_b32_e32 v134, 4, v153
	v_and_b32_e32 v144, 0xf0, v134
	v_mov_b32_e32 v145, v1
	v_lshlrev_b32_e32 v134, 10, v153
	v_lshl_add_u64 v[132:133], v[132:133], 0, v[144:145]
	v_and_b32_e32 v134, 0x3c000, v134
	v_mov_b32_e32 v135, v1
	v_lshl_add_u64 v[172:173], v[132:133], 0, v[134:135]
	s_mov_b32 s6, 0xe640000
	v_add_co_u32_e64 v132, s[6:7], s6, v172
	v_bfe_u32 v145, v153, 4, 4
	s_nop 0
	v_addc_co_u32_e64 v133, s[6:7], 0, v173, s[6:7]
	s_mov_b32 s6, 0xe680000
	s_nop 0
	v_add_co_u32_e64 v136, s[6:7], s6, v172
	global_load_dwordx4 v[132:135], v[132:133], off
	s_nop 0
	v_addc_co_u32_e64 v137, s[6:7], 0, v173, s[6:7]
	s_mov_b32 s6, 0xe6c0000
	s_nop 0
	v_add_co_u32_e64 v140, s[6:7], s6, v172
	global_load_dwordx4 v[136:139], v[136:137], off
	s_nop 0
	v_addc_co_u32_e64 v141, s[6:7], 0, v173, s[6:7]
	s_mov_b32 s6, 0xe700000
	s_nop 0
	v_add_co_u32_e64 v168, s[6:7], s6, v172
	global_load_dwordx4 v[140:143], v[140:141], off
	s_nop 0
	v_addc_co_u32_e64 v169, s[6:7], 0, v173, s[6:7]
	s_mov_b32 s6, 0xe740000
	s_nop 0
	v_add_co_u32_e64 v192, s[6:7], s6, v172
	global_load_dwordx4 v[168:171], v[168:169], off
	s_nop 0
	v_addc_co_u32_e64 v193, s[6:7], 0, v173, s[6:7]
	s_mov_b32 s6, 0xe780000
	s_nop 0
	v_add_co_u32_e64 v196, s[6:7], s6, v172
	global_load_dwordx4 v[192:195], v[192:193], off
	s_nop 0
	v_addc_co_u32_e64 v197, s[6:7], 0, v173, s[6:7]
	s_mov_b32 s6, 0xe7c0000
	s_nop 0
	v_add_co_u32_e64 v208, s[6:7], s6, v172
	global_load_dwordx4 v[196:199], v[196:197], off
	s_nop 0
	v_addc_co_u32_e64 v209, s[6:7], 0, v173, s[6:7]
	s_mov_b32 s6, 0xe800000
	global_load_dwordx4 v[218:221], v[208:209], off
	v_add_co_u32_e64 v208, s[6:7], s6, v172
	v_mul_u32_u24_e32 v145, 0x108, v145
	s_nop 0
	v_addc_co_u32_e64 v209, s[6:7], 0, v173, s[6:7]
	global_load_dwordx4 v[222:225], v[208:209], off
	v_add3_u32 v153, v149, v144, v145
	s_waitcnt vmcnt(7)
	ds_write2_b64 v153, v[132:133], v[134:135] offset1:1
	v_add_u32_e32 v132, 0x1080, v153
	s_waitcnt vmcnt(6)
	ds_write2_b64 v132, v[136:137], v[138:139] offset1:1
	v_add_u32_e32 v132, 0x2100, v153
	s_waitcnt vmcnt(5)
	ds_write2_b64 v132, v[140:141], v[142:143] offset1:1
	v_add_u32_e32 v132, 0x3180, v153
	s_waitcnt vmcnt(4)
	ds_write2_b64 v132, v[168:169], v[170:171] offset1:1
	v_add_u32_e32 v132, 0x4200, v153
	s_waitcnt vmcnt(3)
	ds_write2_b64 v132, v[192:193], v[194:195] offset1:1
	v_add_u32_e32 v132, 0x5280, v153
	s_waitcnt vmcnt(2)
	ds_write2_b64 v132, v[196:197], v[198:199] offset1:1
	v_add_u32_e32 v132, 0x6300, v153
	s_waitcnt vmcnt(1)
	ds_write2_b64 v132, v[218:219], v[220:221] offset1:1
	v_add_u32_e32 v132, 0x7380, v153
	s_waitcnt vmcnt(0)
	ds_write2_b64 v132, v[222:223], v[224:225] offset1:1
	s_mov_b32 s6, 0xe840000
	v_add_co_u32_e64 v132, s[6:7], s6, v172
	s_nop 1
	v_addc_co_u32_e64 v133, s[6:7], 0, v173, s[6:7]
	s_mov_b32 s6, 0xe880000
	s_nop 0
	v_add_co_u32_e64 v136, s[6:7], s6, v172
	global_load_dwordx4 v[132:135], v[132:133], off
	s_nop 0
	v_addc_co_u32_e64 v137, s[6:7], 0, v173, s[6:7]
	s_mov_b32 s6, 0xe8c0000
	s_nop 0
	v_add_co_u32_e64 v140, s[6:7], s6, v172
	global_load_dwordx4 v[136:139], v[136:137], off
	s_nop 0
	v_addc_co_u32_e64 v141, s[6:7], 0, v173, s[6:7]
	s_mov_b32 s6, 0xe900000
	s_nop 0
	v_add_co_u32_e64 v144, s[6:7], s6, v172
	global_load_dwordx4 v[140:143], v[140:141], off
	s_nop 0
	v_addc_co_u32_e64 v145, s[6:7], 0, v173, s[6:7]
	s_mov_b32 s6, 0xe940000
	global_load_dwordx4 v[168:171], v[144:145], off
	v_add_co_u32_e64 v144, s[6:7], s6, v172
	s_nop 1
	v_addc_co_u32_e64 v145, s[6:7], 0, v173, s[6:7]
	s_mov_b32 s6, 0xe980000
	global_load_dwordx4 v[192:195], v[144:145], off
	v_add_co_u32_e64 v144, s[6:7], s6, v172
	s_nop 1
	v_addc_co_u32_e64 v145, s[6:7], 0, v173, s[6:7]
	s_mov_b32 s6, 0xe9c0000
	global_load_dwordx4 v[196:199], v[144:145], off
	v_add_co_u32_e64 v144, s[6:7], s6, v172
	s_nop 1
	v_addc_co_u32_e64 v145, s[6:7], 0, v173, s[6:7]
	s_mov_b32 s6, 0xea00000
	global_load_dwordx4 v[218:221], v[144:145], off
	v_add_co_u32_e64 v144, s[6:7], s6, v172
	s_nop 1
	v_addc_co_u32_e64 v145, s[6:7], 0, v173, s[6:7]
	global_load_dwordx4 v[222:225], v[144:145], off
	v_add_u32_e32 v144, 0x8400, v153
	s_waitcnt vmcnt(7)
	ds_write2_b64 v144, v[132:133], v[134:135] offset1:1
	v_add_u32_e32 v132, 0x9480, v153
	s_waitcnt vmcnt(6)
	ds_write2_b64 v132, v[136:137], v[138:139] offset1:1
	v_add_u32_e32 v132, 0xa500, v153
	s_waitcnt vmcnt(5)
	ds_write2_b64 v132, v[140:141], v[142:143] offset1:1
	v_add_u32_e32 v132, 0xb580, v153
	s_waitcnt vmcnt(4)
	ds_write2_b64 v132, v[168:169], v[170:171] offset1:1
	v_add_u32_e32 v132, 0xc600, v153
	s_waitcnt vmcnt(3)
	ds_write2_b64 v132, v[192:193], v[194:195] offset1:1
	v_add_u32_e32 v132, 0xd680, v153
	s_waitcnt vmcnt(2)
	ds_write2_b64 v132, v[196:197], v[198:199] offset1:1
	v_add_u32_e32 v132, 0xe700, v153
	s_waitcnt vmcnt(1)
	ds_write2_b64 v132, v[218:219], v[220:221] offset1:1
	v_add_u32_e32 v132, 0xf780, v153
	s_waitcnt vmcnt(0)
	ds_write2_b64 v132, v[222:223], v[224:225] offset1:1
	s_waitcnt lgkmcnt(0)
	s_barrier
	v_lshlrev_b64 v[132:133], 14, v[166:167]
	v_lshl_add_u64 v[132:133], s[64:65], 0, v[132:133]
	v_lshl_add_u64 v[130:131], v[132:133], 0, v[130:131]
	v_mov_b32_e32 v153, v1
	v_lshl_add_u64 v[134:135], v[130:131], 0, v[152:153]
	s_mov_b32 s6, 0xf640000
	v_add_co_u32_e64 v130, s[6:7], s6, v134
	v_mul_f32 v2, v2, v159
	v_mul_f32 v3, v3, v159
	v_mul_f32 v4, v4, v159
	v_mul_f32 v5, v5, v159
	s_nop 1
	v_addc_co_u32_e64 v131, s[6:7], 0, v135, s[6:7]
	v_mul_f32 v6, v6, v159
	v_mul_f32 v7, v7, v159
	v_mul_f32 v8, v8, v159
	v_mul_f32 v9, v9, v159
	v_mul_f32 v10, v10, v159
	v_mul_f32 v11, v11, v159
	v_mul_f32 v12, v12, v159
	v_mul_f32 v13, v13, v159
	v_mul_f32 v14, v14, v159
	v_mul_f32 v15, v15, v159
	v_mul_f32 v16, v16, v159
	v_mul_f32 v17, v17, v159
	v_mul_f32 v18, v18, v159
	v_mul_f32 v19, v19, v159
	v_mul_f32 v20, v20, v159
	v_mul_f32 v21, v21, v159
	v_mul_f32 v22, v22, v159
	v_mul_f32 v23, v23, v159
	v_mul_f32 v24, v24, v159
	v_mul_f32 v25, v25, v159
	v_mul_f32 v26, v26, v159
	v_mul_f32 v27, v27, v159
	v_mul_f32 v28, v28, v159
	v_mul_f32 v29, v29, v159
	v_mul_f32 v30, v30, v159
	v_mul_f32 v31, v31, v159
	v_mul_f32 v32, v32, v159
	v_mul_f32 v33, v33, v159
	v_mul_f32 v34, v34, v159
	v_mul_f32 v35, v35, v159
	v_mul_f32 v36, v36, v159
	v_mul_f32 v37, v37, v159
	v_mul_f32 v38, v38, v159
	v_mul_f32 v39, v39, v159
	v_mul_f32 v40, v40, v159
	v_mul_f32 v41, v41, v159
	v_mul_f32 v42, v42, v159
	v_mul_f32 v43, v43, v159
	v_mul_f32 v44, v44, v159
	v_mul_f32 v45, v45, v159
	v_mul_f32 v46, v46, v159
	v_mul_f32 v47, v47, v159
	v_mul_f32 v48, v48, v159
	v_mul_f32 v49, v49, v159
	v_mul_f32 v50, v50, v159
	v_mul_f32 v51, v51, v159
	v_mul_f32 v52, v52, v159
	v_mul_f32 v53, v53, v159
	v_mul_f32 v54, v54, v159
	v_mul_f32 v55, v55, v159
	v_mul_f32 v56, v56, v159
	v_mul_f32 v57, v57, v159
	v_mul_f32 v58, v58, v159
	v_mul_f32 v59, v59, v159
	v_mul_f32 v60, v60, v159
	v_mul_f32 v61, v61, v159
	v_mul_f32 v62, v62, v159
	v_mul_f32 v63, v63, v159
	v_mul_f32 v64, v64, v159
	v_mul_f32 v65, v65, v159
	v_mul_f32 v66, v66, v159
	v_mul_f32 v67, v67, v159
	v_mul_f32 v68, v68, v159
	v_mul_f32 v69, v69, v159
	v_mul_f32 v70, v70, v159
	v_mul_f32 v71, v71, v159
	v_mul_f32 v72, v72, v159
	v_mul_f32 v73, v73, v159
	v_mul_f32 v74, v74, v159
	v_mul_f32 v75, v75, v159
	v_mul_f32 v76, v76, v159
	v_mul_f32 v77, v77, v159
	v_mul_f32 v78, v78, v159
	v_mul_f32 v79, v79, v159
	v_mul_f32 v80, v80, v159
	v_mul_f32 v81, v81, v159
	v_mul_f32 v82, v82, v159
	v_mul_f32 v83, v83, v159
	v_mul_f32 v84, v84, v159
	v_mul_f32 v85, v85, v159
	v_mul_f32 v86, v86, v159
	v_mul_f32 v87, v87, v159
	v_mul_f32 v88, v88, v159
	v_mul_f32 v89, v89, v159
	v_mul_f32 v90, v90, v159
	v_mul_f32 v91, v91, v159
	v_mul_f32 v92, v92, v159
	v_mul_f32 v93, v93, v159
	v_mul_f32 v94, v94, v159
	v_mul_f32 v95, v95, v159
	v_mul_f32 v96, v96, v159
	v_mul_f32 v97, v97, v159
	v_mul_f32 v98, v98, v159
	v_mul_f32 v99, v99, v159
	v_mul_f32 v100, v100, v159
	v_mul_f32 v101, v101, v159
	v_mul_f32 v102, v102, v159
	v_mul_f32 v103, v103, v159
	v_mul_f32 v104, v104, v159
	v_mul_f32 v105, v105, v159
	v_mul_f32 v106, v106, v159
	v_mul_f32 v107, v107, v159
	v_mul_f32 v108, v108, v159
	v_mul_f32 v109, v109, v159
	v_mul_f32 v110, v110, v159
	v_mul_f32 v111, v111, v159
	v_mul_f32 v112, v112, v159
	v_mul_f32 v113, v113, v159
	v_mul_f32 v114, v114, v159
	v_mul_f32 v115, v115, v159
	v_mul_f32 v116, v116, v159
	v_mul_f32 v117, v117, v159
	v_mul_f32 v118, v118, v159
	v_mul_f32 v119, v119, v159
	v_mul_f32 v120, v120, v159
	v_mul_f32 v121, v121, v159
	v_mul_f32 v122, v122, v159
	v_mul_f32 v123, v123, v159
	v_mul_f32 v124, v124, v159
	v_mul_f32 v125, v125, v159
	v_mul_f32 v126, v126, v159
	v_mul_f32 v127, v127, v159
	v_mul_f32 v128, v128, v159
	v_mul_f32 v129, v129, v159
	s_mov_b64 s[6:7], 0xf640000
	v_lshl_add_u64 v[142:143], v[134:135], 0, s[6:7]
	v_mov_b32_e32 v130, v234
	v_mov_b32_e32 v131, v235
	v_mov_b32_e32 v132, v236
	v_mov_b32_e32 v133, v237
	v_mov_b32_e32 v134, v238
	v_mov_b32_e32 v135, v239
	v_mov_b32_e32 v136, v240
	v_mov_b32_e32 v137, v241
	v_mov_b32_e32 v138, v242
	v_mov_b32_e32 v139, v243
	v_mov_b32_e32 v140, v244
	v_mov_b32_e32 v141, v245
	v_mov_b32_e32 v166, v246
	v_mov_b32_e32 v167, v247
	v_mov_b32_e32 v168, v248
	v_mov_b32_e32 v169, v249
	global_load_dwordx4 v[234:237], v[142:143], off offset:128
	global_load_dwordx4 v[238:241], v[142:143], off offset:160
	global_load_dwordx4 v[242:245], v[142:143], off offset:192
	global_load_dwordx4 v[246:249], v[142:143], off offset:224
	v_fma_f32 v144, 0, v191, v190
	v_add_f32_e32 v145, v190, v191
	v_exp_f32_e32 v144, v144
	v_exp_f32_e32 v145, v145
	v_fmamk_f32 v153, v191, 0x42480000, v190
	s_waitcnt vmcnt(4)
	v_lshlrev_b32_e32 v170, 16, v130
	v_and_b32_e32 v171, 0xffff0000, v130
	v_fma_f32 v130, 2.0, v191, v190
	v_pk_mul_f32 v[144:145], v[144:145], v[170:171]
	v_exp_f32_e32 v170, v130
	v_fmamk_f32 v130, v191, 0x40400000, v190
	v_exp_f32_e32 v171, v130
	v_cvt_pk_bf16_f32 v130, v144, v145
	v_lshlrev_b32_e32 v144, 16, v131
	v_and_b32_e32 v145, 0xffff0000, v131
	v_fma_f32 v131, 4.0, v191, v190
	v_pk_mul_f32 v[144:145], v[170:171], v[144:145]
	v_exp_f32_e32 v170, v131
	v_fmamk_f32 v131, v191, 0x40a00000, v190
	v_exp_f32_e32 v171, v131
	v_cvt_pk_bf16_f32 v131, v144, v145
	v_lshlrev_b32_e32 v144, 16, v132
	v_and_b32_e32 v145, 0xffff0000, v132
	v_fmamk_f32 v132, v191, 0x40c00000, v190
	v_pk_mul_f32 v[144:145], v[170:171], v[144:145]
	v_exp_f32_e32 v170, v132
	v_fmamk_f32 v132, v191, 0x40e00000, v190
	v_exp_f32_e32 v171, v132
	v_cvt_pk_bf16_f32 v132, v144, v145
	v_lshlrev_b32_e32 v144, 16, v133
	v_and_b32_e32 v145, 0xffff0000, v133
	v_fmamk_f32 v133, v191, 0x41800000, v190
	v_pk_mul_f32 v[144:145], v[170:171], v[144:145]
	v_exp_f32_e32 v170, v133
	v_fmamk_f32 v133, v191, 0x41880000, v190
	v_exp_f32_e32 v171, v133
	v_cvt_pk_bf16_f32 v133, v144, v145
	s_waitcnt vmcnt(4)
	v_lshlrev_b32_e32 v144, 16, v134
	v_and_b32_e32 v145, 0xffff0000, v134
	v_fmamk_f32 v134, v191, 0x41900000, v190
	v_pk_mul_f32 v[144:145], v[170:171], v[144:145]
	v_exp_f32_e32 v170, v134
	v_fmamk_f32 v134, v191, 0x41980000, v190
	v_exp_f32_e32 v171, v134
	v_cvt_pk_bf16_f32 v134, v144, v145
	v_lshlrev_b32_e32 v144, 16, v135
	v_and_b32_e32 v145, 0xffff0000, v135
	v_fmamk_f32 v135, v191, 0x41a00000, v190
	v_pk_mul_f32 v[144:145], v[170:171], v[144:145]
	v_exp_f32_e32 v170, v135
	v_fmamk_f32 v135, v191, 0x41a80000, v190
	v_exp_f32_e32 v171, v135
	v_cvt_pk_bf16_f32 v135, v144, v145
	v_lshlrev_b32_e32 v144, 16, v136
	v_and_b32_e32 v145, 0xffff0000, v136
	v_fmamk_f32 v136, v191, 0x41b00000, v190
	v_pk_mul_f32 v[144:145], v[170:171], v[144:145]
	v_exp_f32_e32 v170, v136
	v_fmamk_f32 v136, v191, 0x41b80000, v190
	v_exp_f32_e32 v171, v136
	v_cvt_pk_bf16_f32 v136, v144, v145
	v_lshlrev_b32_e32 v144, 16, v137
	v_and_b32_e32 v145, 0xffff0000, v137
	v_fmamk_f32 v137, v191, 0x42000000, v190
	v_pk_mul_f32 v[144:145], v[170:171], v[144:145]
	v_exp_f32_e32 v170, v137
	v_fmamk_f32 v137, v191, 0x42040000, v190
	v_exp_f32_e32 v171, v137
	v_cvt_pk_bf16_f32 v137, v144, v145
	s_waitcnt vmcnt(4)
	v_lshlrev_b32_e32 v144, 16, v138
	v_and_b32_e32 v145, 0xffff0000, v138
	v_fmamk_f32 v138, v191, 0x42080000, v190
	v_pk_mul_f32 v[144:145], v[170:171], v[144:145]
	v_exp_f32_e32 v170, v138
	v_fmamk_f32 v138, v191, 0x420c0000, v190
	v_exp_f32_e32 v171, v138
	v_cvt_pk_bf16_f32 v138, v144, v145
	v_lshlrev_b32_e32 v144, 16, v139
	v_and_b32_e32 v145, 0xffff0000, v139
	v_fmamk_f32 v139, v191, 0x42100000, v190
	v_pk_mul_f32 v[144:145], v[170:171], v[144:145]
	v_exp_f32_e32 v170, v139
	v_fmamk_f32 v139, v191, 0x42140000, v190
	v_exp_f32_e32 v171, v139
	v_cvt_pk_bf16_f32 v139, v144, v145
	v_lshlrev_b32_e32 v144, 16, v140
	v_and_b32_e32 v145, 0xffff0000, v140
	v_fmamk_f32 v140, v191, 0x42180000, v190
	v_pk_mul_f32 v[144:145], v[170:171], v[144:145]
	v_exp_f32_e32 v170, v140
	v_fmamk_f32 v140, v191, 0x421c0000, v190
	v_exp_f32_e32 v171, v140
	v_cvt_pk_bf16_f32 v140, v144, v145
	v_lshlrev_b32_e32 v144, 16, v141
	v_and_b32_e32 v145, 0xffff0000, v141
	v_fmamk_f32 v141, v191, 0x42400000, v190
	v_pk_mul_f32 v[144:145], v[170:171], v[144:145]
	v_exp_f32_e32 v170, v141
	v_fmamk_f32 v141, v191, 0x42440000, v190
	v_exp_f32_e32 v171, v141
	v_cvt_pk_bf16_f32 v141, v144, v145
	s_waitcnt vmcnt(4)
	v_lshlrev_b32_e32 v144, 16, v166
	v_and_b32_e32 v145, 0xffff0000, v166
	v_pk_mul_f32 v[144:145], v[170:171], v[144:145]
	v_exp_f32_e32 v170, v153
	v_fmamk_f32 v153, v191, 0x424c0000, v190
	v_exp_f32_e32 v171, v153
	v_cvt_pk_bf16_f32 v166, v144, v145
	v_lshlrev_b32_e32 v144, 16, v167
	v_and_b32_e32 v145, 0xffff0000, v167
	v_fmamk_f32 v153, v191, 0x42500000, v190
	v_pk_mul_f32 v[144:145], v[170:171], v[144:145]
	v_exp_f32_e32 v170, v153
	v_fmamk_f32 v153, v191, 0x42540000, v190
	v_exp_f32_e32 v171, v153
	v_cvt_pk_bf16_f32 v167, v144, v145
	v_lshlrev_b32_e32 v144, 16, v168
	v_and_b32_e32 v145, 0xffff0000, v168
	v_fmamk_f32 v153, v191, 0x42580000, v190
	v_pk_mul_f32 v[144:145], v[170:171], v[144:145]
	v_exp_f32_e32 v170, v153
	v_fmamk_f32 v153, v191, 0x425c0000, v190
	v_exp_f32_e32 v171, v153
	v_cvt_pk_bf16_f32 v168, v144, v145
	v_lshlrev_b32_e32 v144, 16, v169
	v_and_b32_e32 v145, 0xffff0000, v169
	v_pk_mul_f32 v[144:145], v[170:171], v[144:145]
	s_nop 0
	v_cvt_pk_bf16_f32 v169, v144, v145
	ds_read2_b64 v[170:173], v179 offset1:1
	ds_read2_b64 v[192:195], v179 offset0:4 offset1:5
	ds_read2_b64 v[196:199], v179 offset0:8 offset1:9
	ds_read2_b64 v[218:221], v179 offset0:12 offset1:13
	s_waitcnt lgkmcnt(3)
	v_mfma_f32_32x32x16_bf16 v[2:17], v[170:173], v[130:133], v[2:17]
	v_add_u32_e32 v144, 0x2100, v179
	ds_read2_b64 v[170:173], v144 offset1:1
	s_waitcnt lgkmcnt(3)
	v_mfma_f32_32x32x16_bf16 v[2:17], v[192:195], v[134:137], v[2:17]
	v_add_u32_e32 v144, 0x2120, v179
	ds_read2_b64 v[192:195], v144 offset1:1
	s_waitcnt lgkmcnt(3)
	v_mfma_f32_32x32x16_bf16 v[2:17], v[196:199], v[138:141], v[2:17]
	v_add_u32_e32 v144, 0x2140, v179
	ds_read2_b64 v[196:199], v144 offset1:1
	s_waitcnt lgkmcnt(3)
	v_mfma_f32_32x32x16_bf16 v[2:17], v[218:221], v[166:169], v[2:17]
	v_add_u32_e32 v144, 0x2160, v179
	ds_read2_b64 v[218:221], v144 offset1:1
	s_waitcnt lgkmcnt(3)
	v_mfma_f32_32x32x16_bf16 v[18:33], v[170:173], v[130:133], v[18:33]
	v_add_u32_e32 v144, 0x4200, v179
	ds_read2_b64 v[170:173], v144 offset1:1
	s_waitcnt lgkmcnt(3)
	v_mfma_f32_32x32x16_bf16 v[18:33], v[192:195], v[134:137], v[18:33]
	v_add_u32_e32 v144, 0x4220, v179
	ds_read2_b64 v[192:195], v144 offset1:1
	s_waitcnt lgkmcnt(3)
	v_mfma_f32_32x32x16_bf16 v[18:33], v[196:199], v[138:141], v[18:33]
	v_add_u32_e32 v144, 0x4240, v179
	ds_read2_b64 v[196:199], v144 offset1:1
	s_waitcnt lgkmcnt(3)
	v_mfma_f32_32x32x16_bf16 v[18:33], v[218:221], v[166:169], v[18:33]
	v_add_u32_e32 v144, 0x4260, v179
	ds_read2_b64 v[218:221], v144 offset1:1
	s_waitcnt lgkmcnt(3)
	v_mfma_f32_32x32x16_bf16 v[34:49], v[170:173], v[130:133], v[34:49]
	v_add_u32_e32 v144, 0x6300, v179
	ds_read2_b64 v[170:173], v144 offset1:1
	s_waitcnt lgkmcnt(3)
	v_mfma_f32_32x32x16_bf16 v[34:49], v[192:195], v[134:137], v[34:49]
	v_add_u32_e32 v144, 0x6320, v179
	ds_read2_b64 v[192:195], v144 offset1:1
	s_waitcnt lgkmcnt(3)
	v_mfma_f32_32x32x16_bf16 v[34:49], v[196:199], v[138:141], v[34:49]
	v_add_u32_e32 v144, 0x6340, v179
	ds_read2_b64 v[196:199], v144 offset1:1
	s_waitcnt lgkmcnt(3)
	v_mfma_f32_32x32x16_bf16 v[34:49], v[218:221], v[166:169], v[34:49]
	v_add_u32_e32 v144, 0x6360, v179
	ds_read2_b64 v[218:221], v144 offset1:1
	s_waitcnt lgkmcnt(3)
	v_mfma_f32_32x32x16_bf16 v[50:65], v[170:173], v[130:133], v[50:65]
	v_add_u32_e32 v144, 0x8400, v179
	ds_read2_b64 v[170:173], v144 offset1:1
	s_waitcnt lgkmcnt(3)
	v_mfma_f32_32x32x16_bf16 v[50:65], v[192:195], v[134:137], v[50:65]
	v_add_u32_e32 v144, 0x8420, v179
	ds_read2_b64 v[192:195], v144 offset1:1
	s_waitcnt lgkmcnt(3)
	v_mfma_f32_32x32x16_bf16 v[50:65], v[196:199], v[138:141], v[50:65]
	v_add_u32_e32 v144, 0x8440, v179
	ds_read2_b64 v[196:199], v144 offset1:1
	s_waitcnt lgkmcnt(3)
	v_mfma_f32_32x32x16_bf16 v[50:65], v[218:221], v[166:169], v[50:65]
	v_add_u32_e32 v144, 0x8460, v179
	ds_read2_b64 v[218:221], v144 offset1:1
	s_waitcnt lgkmcnt(3)
	v_mfma_f32_32x32x16_bf16 v[66:81], v[170:173], v[130:133], v[66:81]
	v_add_u32_e32 v144, 0xa500, v179
	ds_read2_b64 v[170:173], v144 offset1:1
	s_waitcnt lgkmcnt(3)
	v_mfma_f32_32x32x16_bf16 v[66:81], v[192:195], v[134:137], v[66:81]
	v_add_u32_e32 v144, 0xa520, v179
	ds_read2_b64 v[192:195], v144 offset1:1
	s_waitcnt lgkmcnt(3)
	v_mfma_f32_32x32x16_bf16 v[66:81], v[196:199], v[138:141], v[66:81]
	v_add_u32_e32 v144, 0xa540, v179
	ds_read2_b64 v[196:199], v144 offset1:1
	s_waitcnt lgkmcnt(3)
	v_mfma_f32_32x32x16_bf16 v[66:81], v[218:221], v[166:169], v[66:81]
	v_add_u32_e32 v144, 0xa560, v179
	ds_read2_b64 v[218:221], v144 offset1:1
	s_waitcnt lgkmcnt(3)
	v_mfma_f32_32x32x16_bf16 v[82:97], v[170:173], v[130:133], v[82:97]
	v_add_u32_e32 v144, 0xc600, v179
	ds_read2_b64 v[170:173], v144 offset1:1
	s_waitcnt lgkmcnt(3)
	v_mfma_f32_32x32x16_bf16 v[82:97], v[192:195], v[134:137], v[82:97]
	v_add_u32_e32 v144, 0xc620, v179
	ds_read2_b64 v[192:195], v144 offset1:1
	s_waitcnt lgkmcnt(3)
	v_mfma_f32_32x32x16_bf16 v[82:97], v[196:199], v[138:141], v[82:97]
	v_add_u32_e32 v144, 0xc640, v179
	ds_read2_b64 v[196:199], v144 offset1:1
	s_waitcnt lgkmcnt(3)
	v_mfma_f32_32x32x16_bf16 v[82:97], v[218:221], v[166:169], v[82:97]
	v_add_u32_e32 v144, 0xc660, v179
	ds_read2_b64 v[218:221], v144 offset1:1
	s_waitcnt lgkmcnt(3)
	v_mfma_f32_32x32x16_bf16 v[98:113], v[170:173], v[130:133], v[98:113]
	v_add_u32_e32 v144, 0xe700, v179
	ds_read2_b64 v[170:173], v144 offset1:1
	s_waitcnt lgkmcnt(3)
	v_mfma_f32_32x32x16_bf16 v[98:113], v[192:195], v[134:137], v[98:113]
	v_add_u32_e32 v144, 0xe720, v179
	ds_read2_b64 v[192:195], v144 offset1:1
	s_waitcnt lgkmcnt(3)
	v_mfma_f32_32x32x16_bf16 v[98:113], v[196:199], v[138:141], v[98:113]
	v_add_u32_e32 v144, 0xe740, v179
	ds_read2_b64 v[196:199], v144 offset1:1
	s_waitcnt lgkmcnt(3)
	v_mfma_f32_32x32x16_bf16 v[98:113], v[218:221], v[166:169], v[98:113]
	v_add_u32_e32 v144, 0xe760, v179
	ds_read2_b64 v[218:221], v144 offset1:1
	s_waitcnt lgkmcnt(3)
	v_mfma_f32_32x32x16_bf16 v[114:129], v[170:173], v[130:133], v[114:129]
	s_waitcnt lgkmcnt(2)
	v_mfma_f32_32x32x16_bf16 v[114:129], v[192:195], v[134:137], v[114:129]
	s_waitcnt lgkmcnt(1)
	v_mfma_f32_32x32x16_bf16 v[114:129], v[196:199], v[138:141], v[114:129]
	s_waitcnt lgkmcnt(0)
	v_mfma_f32_32x32x16_bf16 v[114:129], v[218:221], v[166:169], v[114:129]
	v_fmamk_f32 v134, v191, 0x42800000, v190
	v_fmamk_f32 v135, v191, 0x42820000, v190
	v_exp_f32_e32 v134, v134
	v_exp_f32_e32 v135, v135
	v_fmamk_f32 v138, v191, 0x42a00000, v190
	v_fmamk_f32 v139, v191, 0x42a20000, v190
	v_exp_f32_e32 v138, v138
	v_exp_f32_e32 v139, v139
	v_fmamk_f32 v144, v191, 0x42c00000, v190
	v_fmamk_f32 v145, v191, 0x42c20000, v190
	v_exp_f32_e32 v144, v144
	v_exp_f32_e32 v145, v145
	v_fmamk_f32 v153, v191, 0x42e00000, v190
	s_waitcnt vmcnt(0)
	v_mov_b32_e32 v130, v234
	v_mov_b32_e32 v131, v235
	v_mov_b32_e32 v132, v236
	v_mov_b32_e32 v133, v237
	v_lshlrev_b32_e32 v136, 16, v130
	v_and_b32_e32 v137, 0xffff0000, v130
	v_pk_mul_f32 v[134:135], v[134:135], v[136:137]
	v_lshlrev_b32_e32 v136, 16, v131
	v_cvt_pk_bf16_f32 v130, v134, v135
	v_fmamk_f32 v134, v191, 0x42840000, v190
	v_fmamk_f32 v135, v191, 0x42860000, v190
	v_exp_f32_e32 v134, v134
	v_exp_f32_e32 v135, v135
	v_and_b32_e32 v137, 0xffff0000, v131
	v_pk_mul_f32 v[134:135], v[134:135], v[136:137]
	s_nop 0
	v_cvt_pk_bf16_f32 v131, v134, v135
	v_fmamk_f32 v134, v191, 0x42880000, v190
	v_fmamk_f32 v135, v191, 0x428a0000, v190
	v_exp_f32_e32 v134, v134
	v_exp_f32_e32 v135, v135
	v_lshlrev_b32_e32 v136, 16, v132
	v_and_b32_e32 v137, 0xffff0000, v132
	v_pk_mul_f32 v[134:135], v[134:135], v[136:137]
	s_nop 0
	v_cvt_pk_bf16_f32 v132, v134, v135
	v_fmamk_f32 v134, v191, 0x428c0000, v190
	v_fmamk_f32 v135, v191, 0x428e0000, v190
	v_exp_f32_e32 v134, v134
	v_exp_f32_e32 v135, v135
	v_lshlrev_b32_e32 v136, 16, v133
	v_and_b32_e32 v137, 0xffff0000, v133
	v_pk_mul_f32 v[134:135], v[134:135], v[136:137]
	s_nop 0
	v_cvt_pk_bf16_f32 v133, v134, v135
	s_waitcnt vmcnt(0)
	v_mov_b32_e32 v134, v238
	v_mov_b32_e32 v135, v239
	v_mov_b32_e32 v136, v240
	v_mov_b32_e32 v137, v241
	v_lshlrev_b32_e32 v140, 16, v134
	v_and_b32_e32 v141, 0xffff0000, v134
	v_pk_mul_f32 v[138:139], v[138:139], v[140:141]
	v_lshlrev_b32_e32 v140, 16, v135
	v_cvt_pk_bf16_f32 v134, v138, v139
	v_fmamk_f32 v138, v191, 0x42a40000, v190
	v_fmamk_f32 v139, v191, 0x42a60000, v190
	v_exp_f32_e32 v138, v138
	v_exp_f32_e32 v139, v139
	v_and_b32_e32 v141, 0xffff0000, v135
	v_pk_mul_f32 v[138:139], v[138:139], v[140:141]
	s_nop 0
	v_cvt_pk_bf16_f32 v135, v138, v139
	v_fmamk_f32 v138, v191, 0x42a80000, v190
	v_fmamk_f32 v139, v191, 0x42aa0000, v190
	v_exp_f32_e32 v138, v138
	v_exp_f32_e32 v139, v139
	v_lshlrev_b32_e32 v140, 16, v136
	v_and_b32_e32 v141, 0xffff0000, v136
	v_pk_mul_f32 v[138:139], v[138:139], v[140:141]
	s_nop 0
	v_cvt_pk_bf16_f32 v136, v138, v139
	v_fmamk_f32 v138, v191, 0x42ac0000, v190
	v_fmamk_f32 v139, v191, 0x42ae0000, v190
	v_exp_f32_e32 v138, v138
	v_exp_f32_e32 v139, v139
	v_lshlrev_b32_e32 v140, 16, v137
	v_and_b32_e32 v141, 0xffff0000, v137
	v_pk_mul_f32 v[138:139], v[138:139], v[140:141]
	s_nop 0
	v_cvt_pk_bf16_f32 v137, v138, v139
	s_waitcnt vmcnt(0)
	v_mov_b32_e32 v138, v242
	v_mov_b32_e32 v139, v243
	v_mov_b32_e32 v140, v244
	v_mov_b32_e32 v141, v245
	v_lshlrev_b32_e32 v166, 16, v138
	v_and_b32_e32 v167, 0xffff0000, v138
	v_pk_mul_f32 v[144:145], v[144:145], v[166:167]
	v_lshlrev_b32_e32 v166, 16, v139
	v_cvt_pk_bf16_f32 v138, v144, v145
	v_fmamk_f32 v144, v191, 0x42c40000, v190
	v_fmamk_f32 v145, v191, 0x42c60000, v190
	v_exp_f32_e32 v144, v144
	v_exp_f32_e32 v145, v145
	v_and_b32_e32 v167, 0xffff0000, v139
	v_pk_mul_f32 v[144:145], v[144:145], v[166:167]
	s_nop 0
	v_cvt_pk_bf16_f32 v139, v144, v145
	v_fmamk_f32 v144, v191, 0x42c80000, v190
	v_fmamk_f32 v145, v191, 0x42ca0000, v190
	v_exp_f32_e32 v144, v144
	v_exp_f32_e32 v145, v145
	v_lshlrev_b32_e32 v166, 16, v140
	v_and_b32_e32 v167, 0xffff0000, v140
	v_pk_mul_f32 v[144:145], v[144:145], v[166:167]
	s_nop 0
	v_cvt_pk_bf16_f32 v140, v144, v145
	v_fmamk_f32 v144, v191, 0x42cc0000, v190
	v_fmamk_f32 v145, v191, 0x42ce0000, v190
	v_exp_f32_e32 v144, v144
	v_exp_f32_e32 v145, v145
	v_lshlrev_b32_e32 v166, 16, v141
	v_and_b32_e32 v167, 0xffff0000, v141
	v_pk_mul_f32 v[144:145], v[144:145], v[166:167]
	s_nop 0
	v_cvt_pk_bf16_f32 v141, v144, v145
	v_exp_f32_e32 v166, v153
	v_fmamk_f32 v153, v191, 0x42e20000, v190
	v_exp_f32_e32 v167, v153
	v_fmamk_f32 v153, v191, 0x42e40000, v190
	s_waitcnt vmcnt(0)
	v_mov_b32_e32 v142, v246
	v_mov_b32_e32 v143, v247
	v_mov_b32_e32 v144, v248
	v_mov_b32_e32 v145, v249
	v_lshlrev_b32_e32 v168, 16, v142
	v_and_b32_e32 v169, 0xffff0000, v142
	v_pk_mul_f32 v[166:167], v[166:167], v[168:169]
	v_lshlrev_b32_e32 v168, 16, v143
	v_cvt_pk_bf16_f32 v142, v166, v167
	v_exp_f32_e32 v166, v153
	v_fmamk_f32 v153, v191, 0x42e60000, v190
	v_exp_f32_e32 v167, v153
	v_and_b32_e32 v169, 0xffff0000, v143
	v_fmamk_f32 v153, v191, 0x42e80000, v190
	v_pk_mul_f32 v[166:167], v[166:167], v[168:169]
	s_nop 0
	v_cvt_pk_bf16_f32 v143, v166, v167
	v_exp_f32_e32 v166, v153
	v_fmamk_f32 v153, v191, 0x42ea0000, v190
	v_exp_f32_e32 v167, v153
	v_lshlrev_b32_e32 v168, 16, v144
	v_and_b32_e32 v169, 0xffff0000, v144
	v_fmamk_f32 v153, v191, 0x42ec0000, v190
	v_pk_mul_f32 v[166:167], v[166:167], v[168:169]
	v_fmac_f32_e32 v190, 0x42ee0000, v191
	v_cvt_pk_bf16_f32 v144, v166, v167
	v_exp_f32_e32 v166, v153
	v_exp_f32_e32 v167, v190
	v_lshlrev_b32_e32 v168, 16, v145
	v_and_b32_e32 v169, 0xffff0000, v145
	v_pk_mul_f32 v[166:167], v[166:167], v[168:169]
	s_nop 0
	v_cvt_pk_bf16_f32 v145, v166, v167
	ds_read2_b64 v[166:169], v179 offset0:16 offset1:17
	ds_read2_b64 v[170:173], v179 offset0:20 offset1:21
	ds_read2_b64 v[190:193], v179 offset0:24 offset1:25
	ds_read2_b64 v[194:197], v179 offset0:28 offset1:29
	s_waitcnt lgkmcnt(3)
	v_mfma_f32_32x32x16_bf16 v[2:17], v[166:169], v[130:133], v[2:17]
	v_add_u32_e32 v153, 0x2180, v179
	ds_read2_b64 v[166:169], v153 offset1:1
	s_waitcnt lgkmcnt(3)
	v_mfma_f32_32x32x16_bf16 v[2:17], v[170:173], v[134:137], v[2:17]
	v_add_u32_e32 v153, 0x21a0, v179
	ds_read2_b64 v[170:173], v153 offset1:1
	s_waitcnt lgkmcnt(3)
	v_mfma_f32_32x32x16_bf16 v[2:17], v[190:193], v[138:141], v[2:17]
	v_add_u32_e32 v153, 0x21c0, v179
	ds_read2_b64 v[190:193], v153 offset1:1
	s_waitcnt lgkmcnt(3)
	v_mfma_f32_32x32x16_bf16 v[2:17], v[194:197], v[142:145], v[2:17]
	v_add_u32_e32 v153, 0x21e0, v179
	ds_read2_b64 v[194:197], v153 offset1:1
	s_waitcnt lgkmcnt(3)
	v_mfma_f32_32x32x16_bf16 v[18:33], v[166:169], v[130:133], v[18:33]
	v_add_u32_e32 v153, 0x4280, v179
	ds_read2_b64 v[166:169], v153 offset1:1
	s_waitcnt lgkmcnt(3)
	v_mfma_f32_32x32x16_bf16 v[18:33], v[170:173], v[134:137], v[18:33]
	v_add_u32_e32 v153, 0x42a0, v179
	ds_read2_b64 v[170:173], v153 offset1:1
	s_waitcnt lgkmcnt(3)
	v_mfma_f32_32x32x16_bf16 v[18:33], v[190:193], v[138:141], v[18:33]
	v_add_u32_e32 v153, 0x42c0, v179
	ds_read2_b64 v[190:193], v153 offset1:1
	s_waitcnt lgkmcnt(3)
	v_mfma_f32_32x32x16_bf16 v[18:33], v[194:197], v[142:145], v[18:33]
	v_add_u32_e32 v153, 0x42e0, v179
	ds_read2_b64 v[194:197], v153 offset1:1
	s_waitcnt lgkmcnt(3)
	v_mfma_f32_32x32x16_bf16 v[34:49], v[166:169], v[130:133], v[34:49]
	v_add_u32_e32 v153, 0x6380, v179
	ds_read2_b64 v[166:169], v153 offset1:1
	s_waitcnt lgkmcnt(3)
	v_mfma_f32_32x32x16_bf16 v[34:49], v[170:173], v[134:137], v[34:49]
	v_add_u32_e32 v153, 0x63a0, v179
	ds_read2_b64 v[170:173], v153 offset1:1
	s_waitcnt lgkmcnt(3)
	v_mfma_f32_32x32x16_bf16 v[34:49], v[190:193], v[138:141], v[34:49]
	v_add_u32_e32 v153, 0x63c0, v179
	ds_read2_b64 v[190:193], v153 offset1:1
	s_waitcnt lgkmcnt(3)
	v_mfma_f32_32x32x16_bf16 v[34:49], v[194:197], v[142:145], v[34:49]
	v_add_u32_e32 v153, 0x63e0, v179
	ds_read2_b64 v[194:197], v153 offset1:1
	s_waitcnt lgkmcnt(3)
	v_mfma_f32_32x32x16_bf16 v[50:65], v[166:169], v[130:133], v[50:65]
	v_add_u32_e32 v153, 0x8480, v179
	ds_read2_b64 v[166:169], v153 offset1:1
	s_waitcnt lgkmcnt(3)
	v_mfma_f32_32x32x16_bf16 v[50:65], v[170:173], v[134:137], v[50:65]
	v_add_u32_e32 v153, 0x84a0, v179
	ds_read2_b64 v[170:173], v153 offset1:1
	s_waitcnt lgkmcnt(3)
	v_mfma_f32_32x32x16_bf16 v[50:65], v[190:193], v[138:141], v[50:65]
	v_add_u32_e32 v153, 0x84c0, v179
	ds_read2_b64 v[190:193], v153 offset1:1
	s_waitcnt lgkmcnt(3)
	v_mfma_f32_32x32x16_bf16 v[50:65], v[194:197], v[142:145], v[50:65]
	v_add_u32_e32 v153, 0x84e0, v179
	ds_read2_b64 v[194:197], v153 offset1:1
	s_waitcnt lgkmcnt(3)
	v_mfma_f32_32x32x16_bf16 v[66:81], v[166:169], v[130:133], v[66:81]
	v_add_u32_e32 v153, 0xa580, v179
	ds_read2_b64 v[166:169], v153 offset1:1
	s_waitcnt lgkmcnt(3)
	v_mfma_f32_32x32x16_bf16 v[66:81], v[170:173], v[134:137], v[66:81]
	v_add_u32_e32 v153, 0xa5a0, v179
	ds_read2_b64 v[170:173], v153 offset1:1
	s_waitcnt lgkmcnt(3)
	v_mfma_f32_32x32x16_bf16 v[66:81], v[190:193], v[138:141], v[66:81]
	v_add_u32_e32 v153, 0xa5c0, v179
	ds_read2_b64 v[190:193], v153 offset1:1
	s_waitcnt lgkmcnt(3)
	v_mfma_f32_32x32x16_bf16 v[66:81], v[194:197], v[142:145], v[66:81]
	v_add_u32_e32 v153, 0xa5e0, v179
	ds_read2_b64 v[194:197], v153 offset1:1
	s_waitcnt lgkmcnt(3)
	v_mfma_f32_32x32x16_bf16 v[82:97], v[166:169], v[130:133], v[82:97]
	v_add_u32_e32 v153, 0xc680, v179
	ds_read2_b64 v[166:169], v153 offset1:1
	s_waitcnt lgkmcnt(3)
	v_mfma_f32_32x32x16_bf16 v[82:97], v[170:173], v[134:137], v[82:97]
	v_add_u32_e32 v153, 0xc6a0, v179
	ds_read2_b64 v[170:173], v153 offset1:1
	s_waitcnt lgkmcnt(3)
	v_mfma_f32_32x32x16_bf16 v[82:97], v[190:193], v[138:141], v[82:97]
	v_add_u32_e32 v153, 0xc6c0, v179
	ds_read2_b64 v[190:193], v153 offset1:1
	s_waitcnt lgkmcnt(3)
	v_mfma_f32_32x32x16_bf16 v[82:97], v[194:197], v[142:145], v[82:97]
	v_add_u32_e32 v153, 0xc6e0, v179
	ds_read2_b64 v[194:197], v153 offset1:1
	s_waitcnt lgkmcnt(3)
	v_mfma_f32_32x32x16_bf16 v[98:113], v[166:169], v[130:133], v[98:113]
	v_add_u32_e32 v153, 0xe780, v179
	ds_read2_b64 v[166:169], v153 offset1:1
	s_waitcnt lgkmcnt(3)
	v_mfma_f32_32x32x16_bf16 v[98:113], v[170:173], v[134:137], v[98:113]
	v_add_u32_e32 v153, 0xe7a0, v179
	ds_read2_b64 v[170:173], v153 offset1:1
	s_waitcnt lgkmcnt(3)
	v_mfma_f32_32x32x16_bf16 v[98:113], v[190:193], v[138:141], v[98:113]
	v_add_u32_e32 v153, 0xe7c0, v179
	ds_read2_b64 v[190:193], v153 offset1:1
	s_waitcnt lgkmcnt(3)
	v_mfma_f32_32x32x16_bf16 v[98:113], v[194:197], v[142:145], v[98:113]
	v_add_u32_e32 v153, 0xe7e0, v179
	ds_read2_b64 v[194:197], v153 offset1:1
	s_waitcnt lgkmcnt(3)
	v_mfma_f32_32x32x16_bf16 v[114:129], v[166:169], v[130:133], v[114:129]
	s_waitcnt lgkmcnt(2)
	v_mfma_f32_32x32x16_bf16 v[114:129], v[170:173], v[134:137], v[114:129]
	s_waitcnt lgkmcnt(1)
	v_mfma_f32_32x32x16_bf16 v[114:129], v[190:193], v[138:141], v[114:129]
	s_waitcnt lgkmcnt(0)
	v_mfma_f32_32x32x16_bf16 v[114:129], v[194:197], v[142:145], v[114:129]
	s_add_i32 s66, s66, 1
	s_add_i32 s67, s67, -1
	s_cmp_eq_u32 s67, -1
	s_cbranch_scc0 .LBB0_327
	s_and_b64 vcc, exec, s[4:5]
	s_mov_b64 s[4:5], -1
	s_cbranch_vccnz .LBB0_330
	s_mov_b64 s[4:5], 0
